# XA-step deferred conversion by the flat balanced hand-written converter (17.2 items/wave, no per-segment drain) on top of v58
# baseline (speedup 1.0000x reference)
; #define LAS __attribute__((address_space(3)))
; __device__ __forceinline__ void convert_segments(const Args& args, unsigned char* ws, LAS unsigned char* lds, int seg_lo, int seg_hi, int part_lo, int part_hi, int nparts, int wid, int nw, int wave, int lane) {
;     LAS float* scr = (LAS float*)(lds + wave * 16640);
; #pragma unroll 1
;     for (int sI = seg_lo; sI < seg_hi; ++sI) {
;         const Seg sg = seg_at(sI);
;         const int nblk = sg.ncols / 64, nit = (sg.K / 64) * nblk;
;         const float* W = args.in[sg.in_idx] + (size_t)sg.src_l * sg.K * sg.N;
;         bf16* WT = (bf16*)(ws + WS_W + (size_t)sg.layer * LAYER_W + (size_t)sg.wsub_mib * MiB);
;         const int it_lo = (int)((long)nit * part_lo / nparts), it_hi = (int)((long)nit * part_hi / nparts);
;         int it = it_lo + wid;
;         f32x4 v[16];
;         if (it < it_hi) { const int kb = it / nblk, nb = it - kb * nblk; tr_load(W + (size_t)(64 * kb) * sg.N + sg.scol + 64 * nb, sg.N, v, lane); }
; #pragma unroll 1
;         for (; it < it_hi; it += nw) {
;             const int kb = it / nblk, nb = it - kb * nblk;
;             const int drow = sg.ilv ? (256 * (nb >> 1) + 64 * (nb & 1) + sg.drow) : (sg.drow + 64 * nb);
;             tr_to_lds(v, scr, lane);
;             const int itn = it + nw;
;             if (itn < it_hi) { const int kbn = itn / nblk, nbn = itn - kbn * nblk; tr_load(W + (size_t)(64 * kbn) * sg.N + sg.scol + 64 * nbn, sg.N, v, lane); }
;             tr_store(WT + (size_t)drow * sg.K + 64 * kb, sg.K, scr, lane);
;         }
;     }
; }
; template <int LAYER>
; __device__ __forceinline__ void layer_steps(const Args& args, LAS unsigned char* lds, const XcdBarrier& bar, const int lo, const int hi, int& step,
;                                             const int G, const int bx, const int vcu, const int gw, const int NGW, const int wave) {
;     ...
;             if (SLOT_ON && G == 256 && bx >= XA_BUSY_WGS) { OPQ; convert_segments(args, ws, lds, SEG_DEFER, SEG_END, layer == 0 ? 0 : 1, layer == 0 ? 1 : 2, 2, (bx - XA_BUSY_WGS) * NWAVES + wave, (G - XA_BUSY_WGS) * NWAVES, wave, olane); }
.LBB0_904:
	s_cmpk_lg_i32 s88, 0x100
	s_cselect_b64 s[4:5], -1, 0
	s_cmpk_lt_i32 s2, 0x88
	s_cselect_b64 s[6:7], -1, 0
	s_or_b64 s[4:5], s[6:7], s[4:5]
	s_and_b64 vcc, exec, s[4:5]
	s_cbranch_vccnz .LBB0_919
	s_lshl_b32 s4, s2, 3
	s_add_i32 s4, s4, s89
	s_add_i32 s50, s4, 0xfffffbc0
	s_movk_i32 s63, 0x3c0
	s_mov_b32 s61, 26
	s_mov_b32 s70, 22
	s_mov_b32 s23, 0
	v_mbcnt_lo_u32_b32 v160, -1, 0
	v_mbcnt_hi_u32_b32 v160, -1, v160
	v_lshrrev_b32_e32 v161, 4, v160
	v_and_b32_e32 v162, 15, v160
	v_lshlrev_b32_e32 v162, 2, v162
	s_mul_i32 s66, s89, 0x4100
	v_mul_u32_u24_e32 v163, 0x41, v161
	v_add_u32_e32 v163, v163, v162
	v_lshl_add_u32 v163, v163, 2, s66
	v_and_b32_e32 v164, 7, v160
	v_lshrrev_b32_e32 v165, 3, v160
	v_mul_u32_u24_e32 v166, 0x208, v164
	v_add_u32_e32 v166, v166, v165
	v_lshl_add_u32 v166, v166, 2, s66
	v_add_u32_e32 v167, 0x410, v166
	s_load_dwordx2 s[68:69], s[0:1], 0xe8
	s_waitcnt lgkmcnt(0)
cva_nx1:
	s_cmp_lt_u32 s50, s23
	s_cbranch_scc1 cva_nf1
	s_sub_i32 s50, s50, s23
	s_mov_b32 s23, 0
	s_add_i32 s70, s70, 1
	s_cmp_ge_i32 s70, s61
	s_cbranch_scc1 cva_done
	s_mul_i32 s4, s70, 40
	s_getpc_b64 s[6:7]
	s_add_u32 s6, s6, __const._Z6seg_ati.segs@rel32@lo+4
	s_addc_u32 s7, s7, __const._Z6seg_ati.segs@rel32@hi+12
	s_add_u32 s6, s6, s4
	s_addc_u32 s7, s7, 0
	s_load_dwordx8 s[8:15], s[6:7], 0x0
	s_load_dwordx2 s[18:19], s[6:7], 0x20
	s_waitcnt lgkmcnt(0)
	s_lshr_b32 s20, s13, 6
	s_lshr_b32 s21, s11, 6
	s_mul_i32 s22, s20, s21
	s_lshl_b32 s4, s8, 3
	s_load_dwordx2 s[24:25], s[0:1], s4
	s_mul_i32 s5, s11, s10
	s_mul_i32 s5, s5, s9
	s_lshl_b32 s5, s5, 2
	s_lshl_b32 s6, s12, 2
	s_add_u32 s5, s5, s6
	s_waitcnt lgkmcnt(0)
	s_add_u32 s24, s24, s5
	s_addc_u32 s25, s25, 0
	s_mul_i32 s5, s14, 0x1a400000
	s_lshl_b32 s6, s15, 20
	s_add_u32 s5, s5, s6
	s_add_u32 s5, s5, 0x2d400000
	s_add_u32 s26, s68, s5
	s_addc_u32 s27, s69, 0
	s_mov_b32 s41, 0
	s_lshr_b32 s23, s22, 1
	v_mul_lo_u32 v168, v161, s10
	v_add_u32_e32 v168, v168, v162
	v_lshlrev_b32_e32 v168, 2, v168
	s_lshl_b32 s48, s10, 4
	s_branch cva_nx1
cva_nf1:
	s_add_i32 s43, s41, s50
	s_add_i32 s50, s50, s63
	v_cvt_f32_u32_e32 v170, s43
	v_cvt_f32_u32_e32 v171, s20
	v_rcp_f32_e32 v171, v171
	s_nop 1
	v_mul_f32_e32 v170, v170, v171
	v_cvt_u32_f32_e32 v170, v170
	s_nop 1
	v_readfirstlane_b32 s46, v170
	s_mul_i32 s72, s46, s20
	s_sub_i32 s47, s43, s72
	s_cmp_lt_i32 s47, 0
	s_cselect_b32 s72, s20, 0
	s_cselect_b32 s73, 1, 0
	s_add_i32 s47, s47, s72
	s_sub_i32 s46, s46, s73
	s_cmp_ge_i32 s47, s20
	s_cselect_b32 s72, s20, 0
	s_cselect_b32 s73, 1, 0
	s_sub_i32 s47, s47, s72
	s_add_i32 s46, s46, s73
	s_cmp_ge_i32 s47, s20
	s_cselect_b32 s72, s20, 0
	s_cselect_b32 s73, 1, 0
	s_sub_i32 s47, s47, s72
	s_add_i32 s46, s46, s73
	s_mul_i32 s4, s46, s10
	s_add_i32 s4, s4, s47
	s_lshl_b32 s4, s4, 8
	s_add_u32 s56, s24, s4
	s_addc_u32 s57, s25, 0
	s_lshr_b32 s4, s47, 1
	s_lshl_b32 s4, s4, 8
	s_and_b32 s5, s47, 1
	s_lshl_b32 s5, s5, 6
	s_add_i32 s4, s4, s5
	s_lshl_b32 s5, s47, 6
	s_cmp_lg_u32 s19, 0
	s_cselect_b32 s4, s4, s5
	s_add_i32 s4, s4, s18
	s_mul_i32 s4, s4, s11
	s_lshl_b32 s5, s46, 6
	s_add_i32 s4, s4, s5
	s_lshl_b32 s4, s4, 1
	s_add_u32 s74, s26, s4
	s_addc_u32 s75, s27, 0
	s_mov_b32 s76, s11
	global_load_dwordx4 v[0:3], v168, s[56:57]
	s_add_u32 s56, s56, s48
	s_addc_u32 s57, s57, 0
	global_load_dwordx4 v[4:7], v168, s[56:57]
	s_add_u32 s56, s56, s48
	s_addc_u32 s57, s57, 0
	global_load_dwordx4 v[8:11], v168, s[56:57]
	s_add_u32 s56, s56, s48
	s_addc_u32 s57, s57, 0
	global_load_dwordx4 v[12:15], v168, s[56:57]
	s_add_u32 s56, s56, s48
	s_addc_u32 s57, s57, 0
	global_load_dwordx4 v[16:19], v168, s[56:57]
	s_add_u32 s56, s56, s48
	s_addc_u32 s57, s57, 0
	global_load_dwordx4 v[20:23], v168, s[56:57]
	s_add_u32 s56, s56, s48
	s_addc_u32 s57, s57, 0
	global_load_dwordx4 v[24:27], v168, s[56:57]
	s_add_u32 s56, s56, s48
	s_addc_u32 s57, s57, 0
	global_load_dwordx4 v[28:31], v168, s[56:57]
	s_add_u32 s56, s56, s48
	s_addc_u32 s57, s57, 0
	global_load_dwordx4 v[32:35], v168, s[56:57]
	s_add_u32 s56, s56, s48
	s_addc_u32 s57, s57, 0
	global_load_dwordx4 v[36:39], v168, s[56:57]
	s_add_u32 s56, s56, s48
	s_addc_u32 s57, s57, 0
	global_load_dwordx4 v[40:43], v168, s[56:57]
	s_add_u32 s56, s56, s48
	s_addc_u32 s57, s57, 0
	global_load_dwordx4 v[44:47], v168, s[56:57]
	s_add_u32 s56, s56, s48
	s_addc_u32 s57, s57, 0
	global_load_dwordx4 v[48:51], v168, s[56:57]
	s_add_u32 s56, s56, s48
	s_addc_u32 s57, s57, 0
	global_load_dwordx4 v[52:55], v168, s[56:57]
	s_add_u32 s56, s56, s48
	s_addc_u32 s57, s57, 0
	global_load_dwordx4 v[56:59], v168, s[56:57]
	s_add_u32 s56, s56, s48
	s_addc_u32 s57, s57, 0
	global_load_dwordx4 v[60:63], v168, s[56:57]
	s_mov_b32 s58, 1
	s_mov_b32 s59, 0
cva_nx2:
	s_cmp_lt_u32 s50, s23
	s_cbranch_scc1 cva_nf2
	s_sub_i32 s50, s50, s23
	s_mov_b32 s23, 0
	s_add_i32 s70, s70, 1
	s_cmp_ge_i32 s70, s61
	s_cbranch_scc1 cva_pre
	s_mul_i32 s4, s70, 40
	s_getpc_b64 s[6:7]
	s_add_u32 s6, s6, __const._Z6seg_ati.segs@rel32@lo+4
	s_addc_u32 s7, s7, __const._Z6seg_ati.segs@rel32@hi+12
	s_add_u32 s6, s6, s4
	s_addc_u32 s7, s7, 0
	s_load_dwordx8 s[8:15], s[6:7], 0x0
	s_load_dwordx2 s[18:19], s[6:7], 0x20
	s_waitcnt lgkmcnt(0)
	s_lshr_b32 s20, s13, 6
	s_lshr_b32 s21, s11, 6
	s_mul_i32 s22, s20, s21
	s_lshl_b32 s4, s8, 3
	s_load_dwordx2 s[24:25], s[0:1], s4
	s_mul_i32 s5, s11, s10
	s_mul_i32 s5, s5, s9
	s_lshl_b32 s5, s5, 2
	s_lshl_b32 s6, s12, 2
	s_add_u32 s5, s5, s6
	s_waitcnt lgkmcnt(0)
	s_add_u32 s24, s24, s5
	s_addc_u32 s25, s25, 0
	s_mul_i32 s5, s14, 0x1a400000
	s_lshl_b32 s6, s15, 20
	s_add_u32 s5, s5, s6
	s_add_u32 s5, s5, 0x2d400000
	s_add_u32 s26, s68, s5
	s_addc_u32 s27, s69, 0
	s_mov_b32 s41, 0
	s_lshr_b32 s23, s22, 1
	v_mul_lo_u32 v168, v161, s10
	v_add_u32_e32 v168, v168, v162
	v_lshlrev_b32_e32 v168, 2, v168
	s_lshl_b32 s48, s10, 4
	s_branch cva_nx2
; #define LAS __attribute__((address_space(3)))
; #define LDS_WAIT() asm volatile("s_waitcnt lgkmcnt(0)" ::: "memory")
; __device__ __forceinline__ void tr_load(const float* src, int N, f32x4 (&v)[16], int lane) {
;     const int r4 = lane >> 4, c4 = (lane & 15) * 4;
; #pragma unroll
;     for (int i = 0; i < 16; ++i) v[i] = *(const f32x4*)(src + (size_t)(4 * i + r4) * N + c4);
; }
; __device__ __forceinline__ void tr_to_lds(const f32x4 (&v)[16], LAS float* scr, int lane) {
;     const int r4 = lane >> 4, c4 = (lane & 15) * 4;
; #pragma unroll
;     for (int i = 0; i < 16; ++i) { LAS float* s = scr + (4 * i + r4) * 65 + c4; s[0] = v[i].x; s[1] = v[i].y; s[2] = v[i].z; s[3] = v[i].w; }
;     LDS_WAIT(); asm volatile("" ::: "memory");
; }
; __device__ __forceinline__ void convert_segments(const Args& args, unsigned char* ws, LAS unsigned char* lds, int seg_lo, int seg_hi, int part_lo, int part_hi, int nparts, int wid, int nw, int wave, int lane) {
;     ...
;         int it = it_lo + wid;
;         f32x4 v[16];
;         if (it < it_hi) { const int kb = it / nblk, nb = it - kb * nblk; tr_load(W + (size_t)(64 * kb) * sg.N + sg.scol + 64 * nb, sg.N, v, lane); }
; #pragma unroll 1
;         for (; it < it_hi; it += nw) {
;             const int kb = it / nblk, nb = it - kb * nblk;
;             const int drow = sg.ilv ? (256 * (nb >> 1) + 64 * (nb & 1) + sg.drow) : (sg.drow + 64 * nb);
;             tr_to_lds(v, scr, lane);
;             const int itn = it + nw;
;             if (itn < it_hi) { const int kbn = itn / nblk, nbn = itn - kbn * nblk; tr_load(W + (size_t)(64 * kbn) * sg.N + sg.scol + 64 * nbn, sg.N, v, lane); }
;             tr_store(WT + (size_t)drow * sg.K + 64 * kb, sg.K, scr, lane);
cva_nf2:
	s_add_i32 s43, s41, s50
	s_add_i32 s50, s50, s63
	v_cvt_f32_u32_e32 v170, s43
	v_cvt_f32_u32_e32 v171, s20
	v_rcp_f32_e32 v171, v171
	s_nop 1
	v_mul_f32_e32 v170, v170, v171
	v_cvt_u32_f32_e32 v170, v170
	s_nop 1
	v_readfirstlane_b32 s46, v170
	s_mul_i32 s72, s46, s20
	s_sub_i32 s47, s43, s72
	s_cmp_lt_i32 s47, 0
	s_cselect_b32 s72, s20, 0
	s_cselect_b32 s73, 1, 0
	s_add_i32 s47, s47, s72
	s_sub_i32 s46, s46, s73
	s_cmp_ge_i32 s47, s20
	s_cselect_b32 s72, s20, 0
	s_cselect_b32 s73, 1, 0
	s_sub_i32 s47, s47, s72
	s_add_i32 s46, s46, s73
	s_cmp_ge_i32 s47, s20
	s_cselect_b32 s72, s20, 0
	s_cselect_b32 s73, 1, 0
	s_sub_i32 s47, s47, s72
	s_add_i32 s46, s46, s73
	s_mul_i32 s4, s46, s10
	s_add_i32 s4, s4, s47
	s_lshl_b32 s4, s4, 8
	s_add_u32 s56, s24, s4
	s_addc_u32 s57, s25, 0
	s_lshr_b32 s4, s47, 1
	s_lshl_b32 s4, s4, 8
	s_and_b32 s5, s47, 1
	s_lshl_b32 s5, s5, 6
	s_add_i32 s4, s4, s5
	s_lshl_b32 s5, s47, 6
	s_cmp_lg_u32 s19, 0
	s_cselect_b32 s4, s4, s5
	s_add_i32 s4, s4, s18
	s_mul_i32 s4, s4, s11
	s_lshl_b32 s5, s46, 6
	s_add_i32 s4, s4, s5
	s_lshl_b32 s4, s4, 1
	s_add_u32 s78, s26, s4
	s_addc_u32 s79, s27, 0
	s_mov_b32 s77, s11
	global_load_dwordx4 v[64:67], v168, s[56:57]
	s_add_u32 s56, s56, s48
	s_addc_u32 s57, s57, 0
	global_load_dwordx4 v[68:71], v168, s[56:57]
	s_add_u32 s56, s56, s48
	s_addc_u32 s57, s57, 0
	global_load_dwordx4 v[72:75], v168, s[56:57]
	s_add_u32 s56, s56, s48
	s_addc_u32 s57, s57, 0
	global_load_dwordx4 v[76:79], v168, s[56:57]
	s_add_u32 s56, s56, s48
	s_addc_u32 s57, s57, 0
	global_load_dwordx4 v[80:83], v168, s[56:57]
	s_add_u32 s56, s56, s48
	s_addc_u32 s57, s57, 0
	global_load_dwordx4 v[84:87], v168, s[56:57]
	s_add_u32 s56, s56, s48
	s_addc_u32 s57, s57, 0
	global_load_dwordx4 v[88:91], v168, s[56:57]
	s_add_u32 s56, s56, s48
	s_addc_u32 s57, s57, 0
	global_load_dwordx4 v[92:95], v168, s[56:57]
	s_add_u32 s56, s56, s48
	s_addc_u32 s57, s57, 0
	global_load_dwordx4 v[96:99], v168, s[56:57]
	s_add_u32 s56, s56, s48
	s_addc_u32 s57, s57, 0
	global_load_dwordx4 v[100:103], v168, s[56:57]
	s_add_u32 s56, s56, s48
	s_addc_u32 s57, s57, 0
	global_load_dwordx4 v[104:107], v168, s[56:57]
	s_add_u32 s56, s56, s48
	s_addc_u32 s57, s57, 0
	global_load_dwordx4 v[108:111], v168, s[56:57]
	s_add_u32 s56, s56, s48
	s_addc_u32 s57, s57, 0
	global_load_dwordx4 v[112:115], v168, s[56:57]
	s_add_u32 s56, s56, s48
	s_addc_u32 s57, s57, 0
	global_load_dwordx4 v[116:119], v168, s[56:57]
	s_add_u32 s56, s56, s48
	s_addc_u32 s57, s57, 0
	global_load_dwordx4 v[120:123], v168, s[56:57]
	s_add_u32 s56, s56, s48
	s_addc_u32 s57, s57, 0
	global_load_dwordx4 v[124:127], v168, s[56:57]
	s_mov_b32 s59, 1
cva_pre:
	s_waitcnt vmcnt(0)
cva_stepA:
	s_cmp_lg_u32 s59, 0
	s_cbranch_scc0 cva_w0A
	s_waitcnt vmcnt(32)
	s_branch cva_goA
cva_w0A:
	s_waitcnt vmcnt(0)
cva_goA:
	ds_write_b32 v163, v0 offset:0
	ds_write_b32 v163, v1 offset:4
	ds_write_b32 v163, v2 offset:8
	ds_write_b32 v163, v3 offset:12
	ds_write_b32 v163, v4 offset:1040
	ds_write_b32 v163, v5 offset:1044
	ds_write_b32 v163, v6 offset:1048
	ds_write_b32 v163, v7 offset:1052
	ds_write_b32 v163, v8 offset:2080
	ds_write_b32 v163, v9 offset:2084
	ds_write_b32 v163, v10 offset:2088
	ds_write_b32 v163, v11 offset:2092
	ds_write_b32 v163, v12 offset:3120
	ds_write_b32 v163, v13 offset:3124
	ds_write_b32 v163, v14 offset:3128
	ds_write_b32 v163, v15 offset:3132
	ds_write_b32 v163, v16 offset:4160
	ds_write_b32 v163, v17 offset:4164
	ds_write_b32 v163, v18 offset:4168
	ds_write_b32 v163, v19 offset:4172
	ds_write_b32 v163, v20 offset:5200
	ds_write_b32 v163, v21 offset:5204
	ds_write_b32 v163, v22 offset:5208
	ds_write_b32 v163, v23 offset:5212
	ds_write_b32 v163, v24 offset:6240
	ds_write_b32 v163, v25 offset:6244
	ds_write_b32 v163, v26 offset:6248
	ds_write_b32 v163, v27 offset:6252
	ds_write_b32 v163, v28 offset:7280
	ds_write_b32 v163, v29 offset:7284
	ds_write_b32 v163, v30 offset:7288
	ds_write_b32 v163, v31 offset:7292
	ds_write_b32 v163, v32 offset:8320
	ds_write_b32 v163, v33 offset:8324
	ds_write_b32 v163, v34 offset:8328
	ds_write_b32 v163, v35 offset:8332
	ds_write_b32 v163, v36 offset:9360
	ds_write_b32 v163, v37 offset:9364
	ds_write_b32 v163, v38 offset:9368
	ds_write_b32 v163, v39 offset:9372
	ds_write_b32 v163, v40 offset:10400
	ds_write_b32 v163, v41 offset:10404
	ds_write_b32 v163, v42 offset:10408
	ds_write_b32 v163, v43 offset:10412
	ds_write_b32 v163, v44 offset:11440
	ds_write_b32 v163, v45 offset:11444
	ds_write_b32 v163, v46 offset:11448
	ds_write_b32 v163, v47 offset:11452
	ds_write_b32 v163, v48 offset:12480
	ds_write_b32 v163, v49 offset:12484
	ds_write_b32 v163, v50 offset:12488
	ds_write_b32 v163, v51 offset:12492
	ds_write_b32 v163, v52 offset:13520
	ds_write_b32 v163, v53 offset:13524
	ds_write_b32 v163, v54 offset:13528
	ds_write_b32 v163, v55 offset:13532
	ds_write_b32 v163, v56 offset:14560
	ds_write_b32 v163, v57 offset:14564
	ds_write_b32 v163, v58 offset:14568
	ds_write_b32 v163, v59 offset:14572
	ds_write_b32 v163, v60 offset:15600
	ds_write_b32 v163, v61 offset:15604
	ds_write_b32 v163, v62 offset:15608
	ds_write_b32 v163, v63 offset:15612
	s_waitcnt lgkmcnt(0)
	s_mov_b32 s54, s74
	s_mov_b32 s55, s75
	s_lshl_b32 s49, s76, 4
	v_mul_lo_u32 v169, v165, s76
	v_lshl_add_u32 v169, v164, 3, v169
	v_lshlrev_b32_e32 v169, 1, v169
	s_mov_b32 s58, 0
; #define LAS __attribute__((address_space(3)))
; #define LDS_WAIT() asm volatile("s_waitcnt lgkmcnt(0)" ::: "memory")
; __device__ __forceinline__ unsigned pk2(float lo, float hi) { const f32x2c v = {lo, hi}; return __builtin_bit_cast(unsigned, __builtin_convertvector(v, bf16x2c)); }
; __device__ __forceinline__ void tr_store(bf16* dst, int K, const LAS float* scr, int lane) {
;     const int c = lane & 7;
; #pragma unroll
;     for (int j = 0; j < 8; ++j) { const int n = (lane >> 3) + 8 * j; const LAS float* s = scr + (8 * c) * 65 + n;
;         v4u o; o.x = pk2(s[0], s[65]); o.y = pk2(s[130], s[195]); o.z = pk2(s[260], s[325]); o.w = pk2(s[390], s[455]);
;         *(v4u*)(dst + (size_t)n * K + 8 * c) = o; }
;     LDS_WAIT(); asm volatile("" ::: "memory");
; }
; __device__ __forceinline__ void convert_segments(const Args& args, unsigned char* ws, LAS unsigned char* lds, int seg_lo, int seg_hi, int part_lo, int part_hi, int nparts, int wid, int nw, int wave, int lane) {
;     ...
;         for (; it < it_hi; it += nw) {
;             const int kb = it / nblk, nb = it - kb * nblk;
;             const int drow = sg.ilv ? (256 * (nb >> 1) + 64 * (nb & 1) + sg.drow) : (sg.drow + 64 * nb);
;             tr_to_lds(v, scr, lane);
;             const int itn = it + nw;
;             if (itn < it_hi) { const int kbn = itn / nblk, nbn = itn - kbn * nblk; tr_load(W + (size_t)(64 * kbn) * sg.N + sg.scol + 64 * nbn, sg.N, v, lane); }
;             tr_store(WT + (size_t)drow * sg.K + 64 * kb, sg.K, scr, lane);
cva_nx3:
	s_cmp_lt_u32 s50, s23
	s_cbranch_scc1 cva_nf3
	s_sub_i32 s50, s50, s23
	s_mov_b32 s23, 0
	s_add_i32 s70, s70, 1
	s_cmp_ge_i32 s70, s61
	s_cbranch_scc1 cva_nlA
	s_mul_i32 s4, s70, 40
	s_getpc_b64 s[6:7]
	s_add_u32 s6, s6, __const._Z6seg_ati.segs@rel32@lo+4
	s_addc_u32 s7, s7, __const._Z6seg_ati.segs@rel32@hi+12
	s_add_u32 s6, s6, s4
	s_addc_u32 s7, s7, 0
	s_load_dwordx8 s[8:15], s[6:7], 0x0
	s_load_dwordx2 s[18:19], s[6:7], 0x20
	s_waitcnt lgkmcnt(0)
	s_lshr_b32 s20, s13, 6
	s_lshr_b32 s21, s11, 6
	s_mul_i32 s22, s20, s21
	s_lshl_b32 s4, s8, 3
	s_load_dwordx2 s[24:25], s[0:1], s4
	s_mul_i32 s5, s11, s10
	s_mul_i32 s5, s5, s9
	s_lshl_b32 s5, s5, 2
	s_lshl_b32 s6, s12, 2
	s_add_u32 s5, s5, s6
	s_waitcnt lgkmcnt(0)
	s_add_u32 s24, s24, s5
	s_addc_u32 s25, s25, 0
	s_mul_i32 s5, s14, 0x1a400000
	s_lshl_b32 s6, s15, 20
	s_add_u32 s5, s5, s6
	s_add_u32 s5, s5, 0x2d400000
	s_add_u32 s26, s68, s5
	s_addc_u32 s27, s69, 0
	s_mov_b32 s41, 0
	s_lshr_b32 s23, s22, 1
	v_mul_lo_u32 v168, v161, s10
	v_add_u32_e32 v168, v168, v162
	v_lshlrev_b32_e32 v168, 2, v168
	s_lshl_b32 s48, s10, 4
	s_branch cva_nx3
cva_nf3:
	s_add_i32 s43, s41, s50
	s_add_i32 s50, s50, s63
	v_cvt_f32_u32_e32 v170, s43
	v_cvt_f32_u32_e32 v171, s20
	v_rcp_f32_e32 v171, v171
	s_nop 1
	v_mul_f32_e32 v170, v170, v171
	v_cvt_u32_f32_e32 v170, v170
	s_nop 1
	v_readfirstlane_b32 s46, v170
	s_mul_i32 s72, s46, s20
	s_sub_i32 s47, s43, s72
	s_cmp_lt_i32 s47, 0
	s_cselect_b32 s72, s20, 0
	s_cselect_b32 s73, 1, 0
	s_add_i32 s47, s47, s72
	s_sub_i32 s46, s46, s73
	s_cmp_ge_i32 s47, s20
	s_cselect_b32 s72, s20, 0
	s_cselect_b32 s73, 1, 0
	s_sub_i32 s47, s47, s72
	s_add_i32 s46, s46, s73
	s_cmp_ge_i32 s47, s20
	s_cselect_b32 s72, s20, 0
	s_cselect_b32 s73, 1, 0
	s_sub_i32 s47, s47, s72
	s_add_i32 s46, s46, s73
	s_mul_i32 s4, s46, s10
	s_add_i32 s4, s4, s47
	s_lshl_b32 s4, s4, 8
	s_add_u32 s56, s24, s4
	s_addc_u32 s57, s25, 0
	s_lshr_b32 s4, s47, 1
	s_lshl_b32 s4, s4, 8
	s_and_b32 s5, s47, 1
	s_lshl_b32 s5, s5, 6
	s_add_i32 s4, s4, s5
	s_lshl_b32 s5, s47, 6
	s_cmp_lg_u32 s19, 0
	s_cselect_b32 s4, s4, s5
	s_add_i32 s4, s4, s18
	s_mul_i32 s4, s4, s11
	s_lshl_b32 s5, s46, 6
	s_add_i32 s4, s4, s5
	s_lshl_b32 s4, s4, 1
	s_add_u32 s74, s26, s4
	s_addc_u32 s75, s27, 0
	s_mov_b32 s76, s11
	global_load_dwordx4 v[0:3], v168, s[56:57]
	s_add_u32 s56, s56, s48
	s_addc_u32 s57, s57, 0
	global_load_dwordx4 v[4:7], v168, s[56:57]
	s_add_u32 s56, s56, s48
	s_addc_u32 s57, s57, 0
	global_load_dwordx4 v[8:11], v168, s[56:57]
	s_add_u32 s56, s56, s48
	s_addc_u32 s57, s57, 0
	global_load_dwordx4 v[12:15], v168, s[56:57]
	s_add_u32 s56, s56, s48
	s_addc_u32 s57, s57, 0
	global_load_dwordx4 v[16:19], v168, s[56:57]
	s_add_u32 s56, s56, s48
	s_addc_u32 s57, s57, 0
	global_load_dwordx4 v[20:23], v168, s[56:57]
	s_add_u32 s56, s56, s48
	s_addc_u32 s57, s57, 0
	global_load_dwordx4 v[24:27], v168, s[56:57]
	s_add_u32 s56, s56, s48
	s_addc_u32 s57, s57, 0
	global_load_dwordx4 v[28:31], v168, s[56:57]
	s_add_u32 s56, s56, s48
	s_addc_u32 s57, s57, 0
	global_load_dwordx4 v[32:35], v168, s[56:57]
	s_add_u32 s56, s56, s48
	s_addc_u32 s57, s57, 0
	global_load_dwordx4 v[36:39], v168, s[56:57]
	s_add_u32 s56, s56, s48
	s_addc_u32 s57, s57, 0
	global_load_dwordx4 v[40:43], v168, s[56:57]
	s_add_u32 s56, s56, s48
	s_addc_u32 s57, s57, 0
	global_load_dwordx4 v[44:47], v168, s[56:57]
	s_add_u32 s56, s56, s48
	s_addc_u32 s57, s57, 0
	global_load_dwordx4 v[48:51], v168, s[56:57]
	s_add_u32 s56, s56, s48
	s_addc_u32 s57, s57, 0
	global_load_dwordx4 v[52:55], v168, s[56:57]
	s_add_u32 s56, s56, s48
	s_addc_u32 s57, s57, 0
	global_load_dwordx4 v[56:59], v168, s[56:57]
	s_add_u32 s56, s56, s48
	s_addc_u32 s57, s57, 0
	global_load_dwordx4 v[60:63], v168, s[56:57]
	s_mov_b32 s58, 1
cva_nlA:
	ds_read2_b32 v[128:129], v166 offset0:0 offset1:65
	ds_read2_b32 v[130:131], v166 offset0:130 offset1:195
	ds_read2_b32 v[132:133], v167 offset0:0 offset1:65
	ds_read2_b32 v[134:135], v167 offset0:130 offset1:195
	ds_read2_b32 v[136:137], v166 offset0:8 offset1:73
	ds_read2_b32 v[138:139], v166 offset0:138 offset1:203
	ds_read2_b32 v[140:141], v167 offset0:8 offset1:73
	ds_read2_b32 v[142:143], v167 offset0:138 offset1:203
	s_waitcnt lgkmcnt(4)
	v_cvt_pk_bf16_f32 v152, v128, v129
	v_cvt_pk_bf16_f32 v153, v130, v131
	v_cvt_pk_bf16_f32 v154, v132, v133
	v_cvt_pk_bf16_f32 v155, v134, v135
	global_store_dwordx4 v169, v[152:155], s[54:55]
	s_add_u32 s54, s54, s49
	s_addc_u32 s55, s55, 0
	ds_read2_b32 v[144:145], v166 offset0:16 offset1:81
	ds_read2_b32 v[146:147], v166 offset0:146 offset1:211
	ds_read2_b32 v[148:149], v167 offset0:16 offset1:81
	ds_read2_b32 v[150:151], v167 offset0:146 offset1:211
	s_waitcnt lgkmcnt(4)
	v_cvt_pk_bf16_f32 v156, v136, v137
	v_cvt_pk_bf16_f32 v157, v138, v139
	v_cvt_pk_bf16_f32 v158, v140, v141
	v_cvt_pk_bf16_f32 v159, v142, v143
	global_store_dwordx4 v169, v[156:159], s[54:55]
	s_add_u32 s54, s54, s49
	s_addc_u32 s55, s55, 0
	ds_read2_b32 v[128:129], v166 offset0:24 offset1:89
	ds_read2_b32 v[130:131], v166 offset0:154 offset1:219
	ds_read2_b32 v[132:133], v167 offset0:24 offset1:89
	ds_read2_b32 v[134:135], v167 offset0:154 offset1:219
	s_waitcnt lgkmcnt(4)
	v_cvt_pk_bf16_f32 v152, v144, v145
	v_cvt_pk_bf16_f32 v153, v146, v147
	v_cvt_pk_bf16_f32 v154, v148, v149
	v_cvt_pk_bf16_f32 v155, v150, v151
	global_store_dwordx4 v169, v[152:155], s[54:55]
	s_add_u32 s54, s54, s49
	s_addc_u32 s55, s55, 0
	ds_read2_b32 v[136:137], v166 offset0:32 offset1:97
	ds_read2_b32 v[138:139], v166 offset0:162 offset1:227
	ds_read2_b32 v[140:141], v167 offset0:32 offset1:97
	ds_read2_b32 v[142:143], v167 offset0:162 offset1:227
	s_waitcnt lgkmcnt(4)
; #define LAS __attribute__((address_space(3)))
; #define LDS_WAIT() asm volatile("s_waitcnt lgkmcnt(0)" ::: "memory")
; __device__ __forceinline__ unsigned pk2(float lo, float hi) { const f32x2c v = {lo, hi}; return __builtin_bit_cast(unsigned, __builtin_convertvector(v, bf16x2c)); }
; __device__ __forceinline__ void tr_to_lds(const f32x4 (&v)[16], LAS float* scr, int lane) {
;     const int r4 = lane >> 4, c4 = (lane & 15) * 4;
; #pragma unroll
;     for (int i = 0; i < 16; ++i) { LAS float* s = scr + (4 * i + r4) * 65 + c4; s[0] = v[i].x; s[1] = v[i].y; s[2] = v[i].z; s[3] = v[i].w; }
;     LDS_WAIT(); asm volatile("" ::: "memory");
; }
; __device__ __forceinline__ void tr_store(bf16* dst, int K, const LAS float* scr, int lane) {
;     const int c = lane & 7;
; #pragma unroll
;     for (int j = 0; j < 8; ++j) { const int n = (lane >> 3) + 8 * j; const LAS float* s = scr + (8 * c) * 65 + n;
;         v4u o; o.x = pk2(s[0], s[65]); o.y = pk2(s[130], s[195]); o.z = pk2(s[260], s[325]); o.w = pk2(s[390], s[455]);
;         *(v4u*)(dst + (size_t)n * K + 8 * c) = o; }
;     LDS_WAIT(); asm volatile("" ::: "memory");
; }
	v_cvt_pk_bf16_f32 v156, v128, v129
	v_cvt_pk_bf16_f32 v157, v130, v131
	v_cvt_pk_bf16_f32 v158, v132, v133
	v_cvt_pk_bf16_f32 v159, v134, v135
	global_store_dwordx4 v169, v[156:159], s[54:55]
	s_add_u32 s54, s54, s49
	s_addc_u32 s55, s55, 0
	ds_read2_b32 v[144:145], v166 offset0:40 offset1:105
	ds_read2_b32 v[146:147], v166 offset0:170 offset1:235
	ds_read2_b32 v[148:149], v167 offset0:40 offset1:105
	ds_read2_b32 v[150:151], v167 offset0:170 offset1:235
	s_waitcnt lgkmcnt(4)
	v_cvt_pk_bf16_f32 v152, v136, v137
	v_cvt_pk_bf16_f32 v153, v138, v139
	v_cvt_pk_bf16_f32 v154, v140, v141
	v_cvt_pk_bf16_f32 v155, v142, v143
	global_store_dwordx4 v169, v[152:155], s[54:55]
	s_add_u32 s54, s54, s49
	s_addc_u32 s55, s55, 0
	ds_read2_b32 v[128:129], v166 offset0:48 offset1:113
	ds_read2_b32 v[130:131], v166 offset0:178 offset1:243
	ds_read2_b32 v[132:133], v167 offset0:48 offset1:113
	ds_read2_b32 v[134:135], v167 offset0:178 offset1:243
	s_waitcnt lgkmcnt(4)
	v_cvt_pk_bf16_f32 v156, v144, v145
	v_cvt_pk_bf16_f32 v157, v146, v147
	v_cvt_pk_bf16_f32 v158, v148, v149
	v_cvt_pk_bf16_f32 v159, v150, v151
	global_store_dwordx4 v169, v[156:159], s[54:55]
	s_add_u32 s54, s54, s49
	s_addc_u32 s55, s55, 0
	ds_read2_b32 v[136:137], v166 offset0:56 offset1:121
	ds_read2_b32 v[138:139], v166 offset0:186 offset1:251
	ds_read2_b32 v[140:141], v167 offset0:56 offset1:121
	ds_read2_b32 v[142:143], v167 offset0:186 offset1:251
	s_waitcnt lgkmcnt(4)
	v_cvt_pk_bf16_f32 v152, v128, v129
	v_cvt_pk_bf16_f32 v153, v130, v131
	v_cvt_pk_bf16_f32 v154, v132, v133
	v_cvt_pk_bf16_f32 v155, v134, v135
	global_store_dwordx4 v169, v[152:155], s[54:55]
	s_add_u32 s54, s54, s49
	s_addc_u32 s55, s55, 0
	s_waitcnt lgkmcnt(0)
	v_cvt_pk_bf16_f32 v156, v136, v137
	v_cvt_pk_bf16_f32 v157, v138, v139
	v_cvt_pk_bf16_f32 v158, v140, v141
	v_cvt_pk_bf16_f32 v159, v142, v143
	global_store_dwordx4 v169, v[156:159], s[54:55]
	s_cmp_lg_u32 s59, 0
	s_cbranch_scc0 cva_done
cva_stepB:
	s_cmp_lg_u32 s58, 0
	s_cbranch_scc0 cva_w0B
	s_waitcnt vmcnt(32)
	s_branch cva_goB
cva_w0B:
	s_waitcnt vmcnt(0)
cva_goB:
	ds_write_b32 v163, v64 offset:0
	ds_write_b32 v163, v65 offset:4
	ds_write_b32 v163, v66 offset:8
	ds_write_b32 v163, v67 offset:12
	ds_write_b32 v163, v68 offset:1040
	ds_write_b32 v163, v69 offset:1044
	ds_write_b32 v163, v70 offset:1048
	ds_write_b32 v163, v71 offset:1052
	ds_write_b32 v163, v72 offset:2080
	ds_write_b32 v163, v73 offset:2084
	ds_write_b32 v163, v74 offset:2088
	ds_write_b32 v163, v75 offset:2092
	ds_write_b32 v163, v76 offset:3120
	ds_write_b32 v163, v77 offset:3124
	ds_write_b32 v163, v78 offset:3128
	ds_write_b32 v163, v79 offset:3132
	ds_write_b32 v163, v80 offset:4160
	ds_write_b32 v163, v81 offset:4164
	ds_write_b32 v163, v82 offset:4168
	ds_write_b32 v163, v83 offset:4172
	ds_write_b32 v163, v84 offset:5200
	ds_write_b32 v163, v85 offset:5204
	ds_write_b32 v163, v86 offset:5208
	ds_write_b32 v163, v87 offset:5212
	ds_write_b32 v163, v88 offset:6240
	ds_write_b32 v163, v89 offset:6244
	ds_write_b32 v163, v90 offset:6248
	ds_write_b32 v163, v91 offset:6252
	ds_write_b32 v163, v92 offset:7280
	ds_write_b32 v163, v93 offset:7284
	ds_write_b32 v163, v94 offset:7288
	ds_write_b32 v163, v95 offset:7292
	ds_write_b32 v163, v96 offset:8320
	ds_write_b32 v163, v97 offset:8324
	ds_write_b32 v163, v98 offset:8328
	ds_write_b32 v163, v99 offset:8332
	ds_write_b32 v163, v100 offset:9360
	ds_write_b32 v163, v101 offset:9364
	ds_write_b32 v163, v102 offset:9368
	ds_write_b32 v163, v103 offset:9372
	ds_write_b32 v163, v104 offset:10400
	ds_write_b32 v163, v105 offset:10404
	ds_write_b32 v163, v106 offset:10408
	ds_write_b32 v163, v107 offset:10412
	ds_write_b32 v163, v108 offset:11440
	ds_write_b32 v163, v109 offset:11444
	ds_write_b32 v163, v110 offset:11448
	ds_write_b32 v163, v111 offset:11452
	ds_write_b32 v163, v112 offset:12480
	ds_write_b32 v163, v113 offset:12484
	ds_write_b32 v163, v114 offset:12488
	ds_write_b32 v163, v115 offset:12492
	ds_write_b32 v163, v116 offset:13520
	ds_write_b32 v163, v117 offset:13524
	ds_write_b32 v163, v118 offset:13528
	ds_write_b32 v163, v119 offset:13532
	ds_write_b32 v163, v120 offset:14560
	ds_write_b32 v163, v121 offset:14564
	ds_write_b32 v163, v122 offset:14568
	ds_write_b32 v163, v123 offset:14572
	ds_write_b32 v163, v124 offset:15600
	ds_write_b32 v163, v125 offset:15604
	ds_write_b32 v163, v126 offset:15608
	ds_write_b32 v163, v127 offset:15612
	s_waitcnt lgkmcnt(0)
	s_mov_b32 s54, s78
	s_mov_b32 s55, s79
	s_lshl_b32 s49, s77, 4
	v_mul_lo_u32 v169, v165, s77
	v_lshl_add_u32 v169, v164, 3, v169
	v_lshlrev_b32_e32 v169, 1, v169
	s_mov_b32 s59, 0
cva_nx4:
	s_cmp_lt_u32 s50, s23
	s_cbranch_scc1 cva_nf4
	s_sub_i32 s50, s50, s23
	s_mov_b32 s23, 0
	s_add_i32 s70, s70, 1
	s_cmp_ge_i32 s70, s61
	s_cbranch_scc1 cva_nlB
	s_mul_i32 s4, s70, 40
	s_getpc_b64 s[6:7]
	s_add_u32 s6, s6, __const._Z6seg_ati.segs@rel32@lo+4
	s_addc_u32 s7, s7, __const._Z6seg_ati.segs@rel32@hi+12
	s_add_u32 s6, s6, s4
	s_addc_u32 s7, s7, 0
	s_load_dwordx8 s[8:15], s[6:7], 0x0
	s_load_dwordx2 s[18:19], s[6:7], 0x20
	s_waitcnt lgkmcnt(0)
	s_lshr_b32 s20, s13, 6
	s_lshr_b32 s21, s11, 6
	s_mul_i32 s22, s20, s21
	s_lshl_b32 s4, s8, 3
	s_load_dwordx2 s[24:25], s[0:1], s4
	s_mul_i32 s5, s11, s10
	s_mul_i32 s5, s5, s9
	s_lshl_b32 s5, s5, 2
	s_lshl_b32 s6, s12, 2
	s_add_u32 s5, s5, s6
	s_waitcnt lgkmcnt(0)
	s_add_u32 s24, s24, s5
	s_addc_u32 s25, s25, 0
	s_mul_i32 s5, s14, 0x1a400000
	s_lshl_b32 s6, s15, 20
	s_add_u32 s5, s5, s6
	s_add_u32 s5, s5, 0x2d400000
	s_add_u32 s26, s68, s5
	s_addc_u32 s27, s69, 0
	s_mov_b32 s41, 0
	s_lshr_b32 s23, s22, 1
	v_mul_lo_u32 v168, v161, s10
	v_add_u32_e32 v168, v168, v162
	v_lshlrev_b32_e32 v168, 2, v168
	s_lshl_b32 s48, s10, 4
	s_branch cva_nx4
; #define LAS __attribute__((address_space(3)))
; #define LDS_WAIT() asm volatile("s_waitcnt lgkmcnt(0)" ::: "memory")
; __device__ __forceinline__ unsigned pk2(float lo, float hi) { const f32x2c v = {lo, hi}; return __builtin_bit_cast(unsigned, __builtin_convertvector(v, bf16x2c)); }
; __device__ __forceinline__ void tr_load(const float* src, int N, f32x4 (&v)[16], int lane) {
;     const int r4 = lane >> 4, c4 = (lane & 15) * 4;
; #pragma unroll
;     for (int i = 0; i < 16; ++i) v[i] = *(const f32x4*)(src + (size_t)(4 * i + r4) * N + c4);
; }
; __device__ __forceinline__ void tr_to_lds(const f32x4 (&v)[16], LAS float* scr, int lane) {
;     const int r4 = lane >> 4, c4 = (lane & 15) * 4;
; #pragma unroll
;     for (int i = 0; i < 16; ++i) { LAS float* s = scr + (4 * i + r4) * 65 + c4; s[0] = v[i].x; s[1] = v[i].y; s[2] = v[i].z; s[3] = v[i].w; }
;     LDS_WAIT(); asm volatile("" ::: "memory");
; }
; __device__ __forceinline__ void tr_store(bf16* dst, int K, const LAS float* scr, int lane) {
;     const int c = lane & 7;
; #pragma unroll
;     for (int j = 0; j < 8; ++j) { const int n = (lane >> 3) + 8 * j; const LAS float* s = scr + (8 * c) * 65 + n;
;         v4u o; o.x = pk2(s[0], s[65]); o.y = pk2(s[130], s[195]); o.z = pk2(s[260], s[325]); o.w = pk2(s[390], s[455]);
;         *(v4u*)(dst + (size_t)n * K + 8 * c) = o; }
;     LDS_WAIT(); asm volatile("" ::: "memory");
; }
cva_nf4:
	s_add_i32 s43, s41, s50
	s_add_i32 s50, s50, s63
	v_cvt_f32_u32_e32 v170, s43
	v_cvt_f32_u32_e32 v171, s20
	v_rcp_f32_e32 v171, v171
	s_nop 1
	v_mul_f32_e32 v170, v170, v171
	v_cvt_u32_f32_e32 v170, v170
	s_nop 1
	v_readfirstlane_b32 s46, v170
	s_mul_i32 s72, s46, s20
	s_sub_i32 s47, s43, s72
	s_cmp_lt_i32 s47, 0
	s_cselect_b32 s72, s20, 0
	s_cselect_b32 s73, 1, 0
	s_add_i32 s47, s47, s72
	s_sub_i32 s46, s46, s73
	s_cmp_ge_i32 s47, s20
	s_cselect_b32 s72, s20, 0
	s_cselect_b32 s73, 1, 0
	s_sub_i32 s47, s47, s72
	s_add_i32 s46, s46, s73
	s_cmp_ge_i32 s47, s20
	s_cselect_b32 s72, s20, 0
	s_cselect_b32 s73, 1, 0
	s_sub_i32 s47, s47, s72
	s_add_i32 s46, s46, s73
	s_mul_i32 s4, s46, s10
	s_add_i32 s4, s4, s47
	s_lshl_b32 s4, s4, 8
	s_add_u32 s56, s24, s4
	s_addc_u32 s57, s25, 0
	s_lshr_b32 s4, s47, 1
	s_lshl_b32 s4, s4, 8
	s_and_b32 s5, s47, 1
	s_lshl_b32 s5, s5, 6
	s_add_i32 s4, s4, s5
	s_lshl_b32 s5, s47, 6
	s_cmp_lg_u32 s19, 0
	s_cselect_b32 s4, s4, s5
	s_add_i32 s4, s4, s18
	s_mul_i32 s4, s4, s11
	s_lshl_b32 s5, s46, 6
	s_add_i32 s4, s4, s5
	s_lshl_b32 s4, s4, 1
	s_add_u32 s78, s26, s4
	s_addc_u32 s79, s27, 0
	s_mov_b32 s77, s11
	global_load_dwordx4 v[64:67], v168, s[56:57]
	s_add_u32 s56, s56, s48
	s_addc_u32 s57, s57, 0
	global_load_dwordx4 v[68:71], v168, s[56:57]
	s_add_u32 s56, s56, s48
	s_addc_u32 s57, s57, 0
	global_load_dwordx4 v[72:75], v168, s[56:57]
	s_add_u32 s56, s56, s48
	s_addc_u32 s57, s57, 0
	global_load_dwordx4 v[76:79], v168, s[56:57]
	s_add_u32 s56, s56, s48
	s_addc_u32 s57, s57, 0
	global_load_dwordx4 v[80:83], v168, s[56:57]
	s_add_u32 s56, s56, s48
	s_addc_u32 s57, s57, 0
	global_load_dwordx4 v[84:87], v168, s[56:57]
	s_add_u32 s56, s56, s48
	s_addc_u32 s57, s57, 0
	global_load_dwordx4 v[88:91], v168, s[56:57]
	s_add_u32 s56, s56, s48
	s_addc_u32 s57, s57, 0
	global_load_dwordx4 v[92:95], v168, s[56:57]
	s_add_u32 s56, s56, s48
	s_addc_u32 s57, s57, 0
	global_load_dwordx4 v[96:99], v168, s[56:57]
	s_add_u32 s56, s56, s48
	s_addc_u32 s57, s57, 0
	global_load_dwordx4 v[100:103], v168, s[56:57]
	s_add_u32 s56, s56, s48
	s_addc_u32 s57, s57, 0
	global_load_dwordx4 v[104:107], v168, s[56:57]
	s_add_u32 s56, s56, s48
	s_addc_u32 s57, s57, 0
	global_load_dwordx4 v[108:111], v168, s[56:57]
	s_add_u32 s56, s56, s48
	s_addc_u32 s57, s57, 0
	global_load_dwordx4 v[112:115], v168, s[56:57]
	s_add_u32 s56, s56, s48
	s_addc_u32 s57, s57, 0
	global_load_dwordx4 v[116:119], v168, s[56:57]
	s_add_u32 s56, s56, s48
	s_addc_u32 s57, s57, 0
	global_load_dwordx4 v[120:123], v168, s[56:57]
	s_add_u32 s56, s56, s48
	s_addc_u32 s57, s57, 0
	global_load_dwordx4 v[124:127], v168, s[56:57]
	s_mov_b32 s59, 1
cva_nlB:
	ds_read2_b32 v[128:129], v166 offset0:0 offset1:65
	ds_read2_b32 v[130:131], v166 offset0:130 offset1:195
	ds_read2_b32 v[132:133], v167 offset0:0 offset1:65
	ds_read2_b32 v[134:135], v167 offset0:130 offset1:195
	ds_read2_b32 v[136:137], v166 offset0:8 offset1:73
	ds_read2_b32 v[138:139], v166 offset0:138 offset1:203
	ds_read2_b32 v[140:141], v167 offset0:8 offset1:73
	ds_read2_b32 v[142:143], v167 offset0:138 offset1:203
	s_waitcnt lgkmcnt(4)
	v_cvt_pk_bf16_f32 v152, v128, v129
	v_cvt_pk_bf16_f32 v153, v130, v131
	v_cvt_pk_bf16_f32 v154, v132, v133
	v_cvt_pk_bf16_f32 v155, v134, v135
	global_store_dwordx4 v169, v[152:155], s[54:55]
	s_add_u32 s54, s54, s49
	s_addc_u32 s55, s55, 0
	ds_read2_b32 v[144:145], v166 offset0:16 offset1:81
	ds_read2_b32 v[146:147], v166 offset0:146 offset1:211
	ds_read2_b32 v[148:149], v167 offset0:16 offset1:81
	ds_read2_b32 v[150:151], v167 offset0:146 offset1:211
	s_waitcnt lgkmcnt(4)
	v_cvt_pk_bf16_f32 v156, v136, v137
	v_cvt_pk_bf16_f32 v157, v138, v139
	v_cvt_pk_bf16_f32 v158, v140, v141
	v_cvt_pk_bf16_f32 v159, v142, v143
	global_store_dwordx4 v169, v[156:159], s[54:55]
	s_add_u32 s54, s54, s49
	s_addc_u32 s55, s55, 0
	ds_read2_b32 v[128:129], v166 offset0:24 offset1:89
	ds_read2_b32 v[130:131], v166 offset0:154 offset1:219
	ds_read2_b32 v[132:133], v167 offset0:24 offset1:89
	ds_read2_b32 v[134:135], v167 offset0:154 offset1:219
	s_waitcnt lgkmcnt(4)
	v_cvt_pk_bf16_f32 v152, v144, v145
	v_cvt_pk_bf16_f32 v153, v146, v147
	v_cvt_pk_bf16_f32 v154, v148, v149
	v_cvt_pk_bf16_f32 v155, v150, v151
	global_store_dwordx4 v169, v[152:155], s[54:55]
	s_add_u32 s54, s54, s49
	s_addc_u32 s55, s55, 0
	ds_read2_b32 v[136:137], v166 offset0:32 offset1:97
	ds_read2_b32 v[138:139], v166 offset0:162 offset1:227
	ds_read2_b32 v[140:141], v167 offset0:32 offset1:97
	ds_read2_b32 v[142:143], v167 offset0:162 offset1:227
	s_waitcnt lgkmcnt(4)
	v_cvt_pk_bf16_f32 v156, v128, v129
	v_cvt_pk_bf16_f32 v157, v130, v131
	v_cvt_pk_bf16_f32 v158, v132, v133
	v_cvt_pk_bf16_f32 v159, v134, v135
	global_store_dwordx4 v169, v[156:159], s[54:55]
	s_add_u32 s54, s54, s49
	s_addc_u32 s55, s55, 0
	ds_read2_b32 v[144:145], v166 offset0:40 offset1:105
	ds_read2_b32 v[146:147], v166 offset0:170 offset1:235
	ds_read2_b32 v[148:149], v167 offset0:40 offset1:105
	ds_read2_b32 v[150:151], v167 offset0:170 offset1:235
	s_waitcnt lgkmcnt(4)
	v_cvt_pk_bf16_f32 v152, v136, v137
	v_cvt_pk_bf16_f32 v153, v138, v139
	v_cvt_pk_bf16_f32 v154, v140, v141
	v_cvt_pk_bf16_f32 v155, v142, v143
	global_store_dwordx4 v169, v[152:155], s[54:55]
	s_add_u32 s54, s54, s49
	s_addc_u32 s55, s55, 0
	ds_read2_b32 v[128:129], v166 offset0:48 offset1:113
	ds_read2_b32 v[130:131], v166 offset0:178 offset1:243
	ds_read2_b32 v[132:133], v167 offset0:48 offset1:113
	ds_read2_b32 v[134:135], v167 offset0:178 offset1:243
	s_waitcnt lgkmcnt(4)
	v_cvt_pk_bf16_f32 v156, v144, v145
	v_cvt_pk_bf16_f32 v157, v146, v147
	v_cvt_pk_bf16_f32 v158, v148, v149
	v_cvt_pk_bf16_f32 v159, v150, v151
	global_store_dwordx4 v169, v[156:159], s[54:55]
	s_add_u32 s54, s54, s49
	s_addc_u32 s55, s55, 0
	ds_read2_b32 v[136:137], v166 offset0:56 offset1:121
	ds_read2_b32 v[138:139], v166 offset0:186 offset1:251
	ds_read2_b32 v[140:141], v167 offset0:56 offset1:121
	ds_read2_b32 v[142:143], v167 offset0:186 offset1:251
	s_waitcnt lgkmcnt(4)
	v_cvt_pk_bf16_f32 v152, v128, v129
	v_cvt_pk_bf16_f32 v153, v130, v131
	v_cvt_pk_bf16_f32 v154, v132, v133
	v_cvt_pk_bf16_f32 v155, v134, v135
	global_store_dwordx4 v169, v[152:155], s[54:55]
	s_add_u32 s54, s54, s49
	s_addc_u32 s55, s55, 0
	s_waitcnt lgkmcnt(0)
	v_cvt_pk_bf16_f32 v156, v136, v137
	v_cvt_pk_bf16_f32 v157, v138, v139
	v_cvt_pk_bf16_f32 v158, v140, v141
	v_cvt_pk_bf16_f32 v159, v142, v143
	global_store_dwordx4 v169, v[156:159], s[54:55]
	s_cmp_lg_u32 s58, 0
	s_cbranch_scc0 cva_done
	s_branch cva_stepA
cva_done:
	s_waitcnt vmcnt(0) lgkmcnt(0)

; #define LAS __attribute__((address_space(3)))
; __device__ __forceinline__ void convert_segments(const Args& args, unsigned char* ws, LAS unsigned char* lds, int seg_lo, int seg_hi, int part_lo, int part_hi, int nparts, int wid, int nw, int wave, int lane) {
;     LAS float* scr = (LAS float*)(lds + wave * 16640);
; #pragma unroll 1
;     for (int sI = seg_lo; sI < seg_hi; ++sI) {
;         const Seg sg = seg_at(sI);
;         const int nblk = sg.ncols / 64, nit = (sg.K / 64) * nblk;
;         const float* W = args.in[sg.in_idx] + (size_t)sg.src_l * sg.K * sg.N;
;         bf16* WT = (bf16*)(ws + WS_W + (size_t)sg.layer * LAYER_W + (size_t)sg.wsub_mib * MiB);
;         const int it_lo = (int)((long)nit * part_lo / nparts), it_hi = (int)((long)nit * part_hi / nparts);
;         int it = it_lo + wid;
;         f32x4 v[16];
;         if (it < it_hi) { const int kb = it / nblk, nb = it - kb * nblk; tr_load(W + (size_t)(64 * kb) * sg.N + sg.scol + 64 * nb, sg.N, v, lane); }
; #pragma unroll 1
;         for (; it < it_hi; it += nw) {
;             const int kb = it / nblk, nb = it - kb * nblk;
;             const int drow = sg.ilv ? (256 * (nb >> 1) + 64 * (nb & 1) + sg.drow) : (sg.drow + 64 * nb);
;             tr_to_lds(v, scr, lane);
;             const int itn = it + nw;
;             if (itn < it_hi) { const int kbn = itn / nblk, nbn = itn - kbn * nblk; tr_load(W + (size_t)(64 * kbn) * sg.N + sg.scol + 64 * nbn, sg.N, v, lane); }
;             tr_store(WT + (size_t)drow * sg.K + 64 * kb, sg.K, scr, lane);
;         }
;     }
; }
; template <int LAYER>
; __device__ __forceinline__ void layer_steps(const Args& args, LAS unsigned char* lds, const XcdBarrier& bar, const int lo, const int hi, int& step,
;                                             const int G, const int bx, const int vcu, const int gw, const int NGW, const int wave) {
;     ...
;             if (SLOT_ON && G == 256 && bx >= XA_BUSY_WGS) { OPQ; convert_segments(args, ws, lds, SEG_DEFER, SEG_END, layer == 0 ? 0 : 1, layer == 0 ? 1 : 2, 2, (bx - XA_BUSY_WGS) * NWAVES + wave, (G - XA_BUSY_WGS) * NWAVES, wave, olane); }
cvb_nx5:
	s_cmp_lt_u32 s50, s23
	s_cbranch_scc1 cvb_nf5
	s_sub_i32 s50, s50, s23
	s_mov_b32 s23, 0
	s_add_i32 s70, s70, 1
	s_cmp_ge_i32 s70, s61
	s_cbranch_scc1 cvb_done
	s_mul_i32 s4, s70, 40
	s_getpc_b64 s[6:7]
	s_add_u32 s6, s6, __const._Z6seg_ati.segs@rel32@lo+4
	s_addc_u32 s7, s7, __const._Z6seg_ati.segs@rel32@hi+12
	s_add_u32 s6, s6, s4
	s_addc_u32 s7, s7, 0
	s_load_dwordx8 s[8:15], s[6:7], 0x0
	s_load_dwordx2 s[18:19], s[6:7], 0x20
	s_waitcnt lgkmcnt(0)
	s_lshr_b32 s20, s13, 6
	s_lshr_b32 s21, s11, 6
	s_mul_i32 s22, s20, s21
	s_lshl_b32 s4, s8, 3
	s_load_dwordx2 s[24:25], s[0:1], s4
	s_mul_i32 s5, s11, s10
	s_mul_i32 s5, s5, s9
	s_lshl_b32 s5, s5, 2
	s_lshl_b32 s6, s12, 2
	s_add_u32 s5, s5, s6
	s_waitcnt lgkmcnt(0)
	s_add_u32 s24, s24, s5
	s_addc_u32 s25, s25, 0
	s_mul_i32 s5, s14, 0x1a400000
	s_lshl_b32 s6, s15, 20
	s_add_u32 s5, s5, s6
	s_add_u32 s5, s5, 0x2d400000
	s_add_u32 s26, s68, s5
	s_addc_u32 s27, s69, 0
	s_lshr_b32 s41, s22, 1
	s_sub_i32 s23, s22, s41
	v_mul_lo_u32 v168, v161, s10
	v_add_u32_e32 v168, v168, v162
	v_lshlrev_b32_e32 v168, 2, v168
	s_lshl_b32 s48, s10, 4
	s_branch cvb_nx5
cvb_nf5:
	s_add_i32 s43, s41, s50
	s_add_i32 s50, s50, s63
	v_cvt_f32_u32_e32 v170, s43
	v_cvt_f32_u32_e32 v171, s20
	v_rcp_f32_e32 v171, v171
	s_nop 1
	v_mul_f32_e32 v170, v170, v171
	v_cvt_u32_f32_e32 v170, v170
	s_nop 1
	v_readfirstlane_b32 s46, v170
	s_mul_i32 s72, s46, s20
	s_sub_i32 s47, s43, s72
	s_cmp_lt_i32 s47, 0
	s_cselect_b32 s72, s20, 0
	s_cselect_b32 s73, 1, 0
	s_add_i32 s47, s47, s72
	s_sub_i32 s46, s46, s73
	s_cmp_ge_i32 s47, s20
	s_cselect_b32 s72, s20, 0
	s_cselect_b32 s73, 1, 0
	s_sub_i32 s47, s47, s72
	s_add_i32 s46, s46, s73
	s_cmp_ge_i32 s47, s20
	s_cselect_b32 s72, s20, 0
	s_cselect_b32 s73, 1, 0
	s_sub_i32 s47, s47, s72
	s_add_i32 s46, s46, s73
	s_mul_i32 s4, s46, s10
	s_add_i32 s4, s4, s47
	s_lshl_b32 s4, s4, 8
	s_add_u32 s56, s24, s4
	s_addc_u32 s57, s25, 0
	s_lshr_b32 s4, s47, 1
	s_lshl_b32 s4, s4, 8
	s_and_b32 s5, s47, 1
	s_lshl_b32 s5, s5, 6
	s_add_i32 s4, s4, s5
	s_lshl_b32 s5, s47, 6
	s_cmp_lg_u32 s19, 0
	s_cselect_b32 s4, s4, s5
	s_add_i32 s4, s4, s18
	s_mul_i32 s4, s4, s11
	s_lshl_b32 s5, s46, 6
	s_add_i32 s4, s4, s5
	s_lshl_b32 s4, s4, 1
	s_add_u32 s74, s26, s4
	s_addc_u32 s75, s27, 0
	s_mov_b32 s76, s11
	global_load_dwordx4 v[0:3], v168, s[56:57]
	s_add_u32 s56, s56, s48
	s_addc_u32 s57, s57, 0
	global_load_dwordx4 v[4:7], v168, s[56:57]
	s_add_u32 s56, s56, s48
	s_addc_u32 s57, s57, 0
	global_load_dwordx4 v[8:11], v168, s[56:57]
	s_add_u32 s56, s56, s48
	s_addc_u32 s57, s57, 0
	global_load_dwordx4 v[12:15], v168, s[56:57]
	s_add_u32 s56, s56, s48
	s_addc_u32 s57, s57, 0
	global_load_dwordx4 v[16:19], v168, s[56:57]
	s_add_u32 s56, s56, s48
	s_addc_u32 s57, s57, 0
	global_load_dwordx4 v[20:23], v168, s[56:57]
	s_add_u32 s56, s56, s48
	s_addc_u32 s57, s57, 0
	global_load_dwordx4 v[24:27], v168, s[56:57]
	s_add_u32 s56, s56, s48
	s_addc_u32 s57, s57, 0
	global_load_dwordx4 v[28:31], v168, s[56:57]
	s_add_u32 s56, s56, s48
	s_addc_u32 s57, s57, 0
	global_load_dwordx4 v[32:35], v168, s[56:57]
	s_add_u32 s56, s56, s48
	s_addc_u32 s57, s57, 0
	global_load_dwordx4 v[36:39], v168, s[56:57]
	s_add_u32 s56, s56, s48
	s_addc_u32 s57, s57, 0
	global_load_dwordx4 v[40:43], v168, s[56:57]
	s_add_u32 s56, s56, s48
	s_addc_u32 s57, s57, 0
	global_load_dwordx4 v[44:47], v168, s[56:57]
	s_add_u32 s56, s56, s48
	s_addc_u32 s57, s57, 0
	global_load_dwordx4 v[48:51], v168, s[56:57]
	s_add_u32 s56, s56, s48
	s_addc_u32 s57, s57, 0
	global_load_dwordx4 v[52:55], v168, s[56:57]
	s_add_u32 s56, s56, s48
	s_addc_u32 s57, s57, 0
	global_load_dwordx4 v[56:59], v168, s[56:57]
	s_add_u32 s56, s56, s48
	s_addc_u32 s57, s57, 0
	global_load_dwordx4 v[60:63], v168, s[56:57]
	s_mov_b32 s58, 1
	s_mov_b32 s59, 0
cvb_nx6:
	s_cmp_lt_u32 s50, s23
	s_cbranch_scc1 cvb_nf6
	s_sub_i32 s50, s50, s23
	s_mov_b32 s23, 0
	s_add_i32 s70, s70, 1
	s_cmp_ge_i32 s70, s61
	s_cbranch_scc1 cvb_pre
	s_mul_i32 s4, s70, 40
	s_getpc_b64 s[6:7]
	s_add_u32 s6, s6, __const._Z6seg_ati.segs@rel32@lo+4
	s_addc_u32 s7, s7, __const._Z6seg_ati.segs@rel32@hi+12
	s_add_u32 s6, s6, s4
	s_addc_u32 s7, s7, 0
	s_load_dwordx8 s[8:15], s[6:7], 0x0
	s_load_dwordx2 s[18:19], s[6:7], 0x20
	s_waitcnt lgkmcnt(0)
	s_lshr_b32 s20, s13, 6
	s_lshr_b32 s21, s11, 6
	s_mul_i32 s22, s20, s21
	s_lshl_b32 s4, s8, 3
	s_load_dwordx2 s[24:25], s[0:1], s4
	s_mul_i32 s5, s11, s10
	s_mul_i32 s5, s5, s9
	s_lshl_b32 s5, s5, 2
	s_lshl_b32 s6, s12, 2
	s_add_u32 s5, s5, s6
	s_waitcnt lgkmcnt(0)
	s_add_u32 s24, s24, s5
	s_addc_u32 s25, s25, 0
	s_mul_i32 s5, s14, 0x1a400000
	s_lshl_b32 s6, s15, 20
	s_add_u32 s5, s5, s6
	s_add_u32 s5, s5, 0x2d400000
	s_add_u32 s26, s68, s5
	s_addc_u32 s27, s69, 0
	s_lshr_b32 s41, s22, 1
	s_sub_i32 s23, s22, s41
	v_mul_lo_u32 v168, v161, s10
	v_add_u32_e32 v168, v168, v162
	v_lshlrev_b32_e32 v168, 2, v168
	s_lshl_b32 s48, s10, 4
	s_branch cvb_nx6
; #define LAS __attribute__((address_space(3)))
; #define LDS_WAIT() asm volatile("s_waitcnt lgkmcnt(0)" ::: "memory")
; __device__ __forceinline__ void tr_load(const float* src, int N, f32x4 (&v)[16], int lane) {
;     const int r4 = lane >> 4, c4 = (lane & 15) * 4;
; #pragma unroll
;     for (int i = 0; i < 16; ++i) v[i] = *(const f32x4*)(src + (size_t)(4 * i + r4) * N + c4);
; }
; __device__ __forceinline__ void tr_to_lds(const f32x4 (&v)[16], LAS float* scr, int lane) {
;     const int r4 = lane >> 4, c4 = (lane & 15) * 4;
; #pragma unroll
;     for (int i = 0; i < 16; ++i) { LAS float* s = scr + (4 * i + r4) * 65 + c4; s[0] = v[i].x; s[1] = v[i].y; s[2] = v[i].z; s[3] = v[i].w; }
;     LDS_WAIT(); asm volatile("" ::: "memory");
; }
; __device__ __forceinline__ void convert_segments(const Args& args, unsigned char* ws, LAS unsigned char* lds, int seg_lo, int seg_hi, int part_lo, int part_hi, int nparts, int wid, int nw, int wave, int lane) {
;     ...
;         int it = it_lo + wid;
;         f32x4 v[16];
;         if (it < it_hi) { const int kb = it / nblk, nb = it - kb * nblk; tr_load(W + (size_t)(64 * kb) * sg.N + sg.scol + 64 * nb, sg.N, v, lane); }
; #pragma unroll 1
;         for (; it < it_hi; it += nw) {
;             const int kb = it / nblk, nb = it - kb * nblk;
;             const int drow = sg.ilv ? (256 * (nb >> 1) + 64 * (nb & 1) + sg.drow) : (sg.drow + 64 * nb);
;             tr_to_lds(v, scr, lane);
;             const int itn = it + nw;
;             if (itn < it_hi) { const int kbn = itn / nblk, nbn = itn - kbn * nblk; tr_load(W + (size_t)(64 * kbn) * sg.N + sg.scol + 64 * nbn, sg.N, v, lane); }
;             tr_store(WT + (size_t)drow * sg.K + 64 * kb, sg.K, scr, lane);
cvb_nf6:
	s_add_i32 s43, s41, s50
	s_add_i32 s50, s50, s63
	v_cvt_f32_u32_e32 v170, s43
	v_cvt_f32_u32_e32 v171, s20
	v_rcp_f32_e32 v171, v171
	s_nop 1
	v_mul_f32_e32 v170, v170, v171
	v_cvt_u32_f32_e32 v170, v170
	s_nop 1
	v_readfirstlane_b32 s46, v170
	s_mul_i32 s72, s46, s20
	s_sub_i32 s47, s43, s72
	s_cmp_lt_i32 s47, 0
	s_cselect_b32 s72, s20, 0
	s_cselect_b32 s73, 1, 0
	s_add_i32 s47, s47, s72
	s_sub_i32 s46, s46, s73
	s_cmp_ge_i32 s47, s20
	s_cselect_b32 s72, s20, 0
	s_cselect_b32 s73, 1, 0
	s_sub_i32 s47, s47, s72
	s_add_i32 s46, s46, s73
	s_cmp_ge_i32 s47, s20
	s_cselect_b32 s72, s20, 0
	s_cselect_b32 s73, 1, 0
	s_sub_i32 s47, s47, s72
	s_add_i32 s46, s46, s73
	s_mul_i32 s4, s46, s10
	s_add_i32 s4, s4, s47
	s_lshl_b32 s4, s4, 8
	s_add_u32 s56, s24, s4
	s_addc_u32 s57, s25, 0
	s_lshr_b32 s4, s47, 1
	s_lshl_b32 s4, s4, 8
	s_and_b32 s5, s47, 1
	s_lshl_b32 s5, s5, 6
	s_add_i32 s4, s4, s5
	s_lshl_b32 s5, s47, 6
	s_cmp_lg_u32 s19, 0
	s_cselect_b32 s4, s4, s5
	s_add_i32 s4, s4, s18
	s_mul_i32 s4, s4, s11
	s_lshl_b32 s5, s46, 6
	s_add_i32 s4, s4, s5
	s_lshl_b32 s4, s4, 1
	s_add_u32 s78, s26, s4
	s_addc_u32 s79, s27, 0
	s_mov_b32 s77, s11
	global_load_dwordx4 v[64:67], v168, s[56:57]
	s_add_u32 s56, s56, s48
	s_addc_u32 s57, s57, 0
	global_load_dwordx4 v[68:71], v168, s[56:57]
	s_add_u32 s56, s56, s48
	s_addc_u32 s57, s57, 0
	global_load_dwordx4 v[72:75], v168, s[56:57]
	s_add_u32 s56, s56, s48
	s_addc_u32 s57, s57, 0
	global_load_dwordx4 v[76:79], v168, s[56:57]
	s_add_u32 s56, s56, s48
	s_addc_u32 s57, s57, 0
	global_load_dwordx4 v[80:83], v168, s[56:57]
	s_add_u32 s56, s56, s48
	s_addc_u32 s57, s57, 0
	global_load_dwordx4 v[84:87], v168, s[56:57]
	s_add_u32 s56, s56, s48
	s_addc_u32 s57, s57, 0
	global_load_dwordx4 v[88:91], v168, s[56:57]
	s_add_u32 s56, s56, s48
	s_addc_u32 s57, s57, 0
	global_load_dwordx4 v[92:95], v168, s[56:57]
	s_add_u32 s56, s56, s48
	s_addc_u32 s57, s57, 0
	global_load_dwordx4 v[96:99], v168, s[56:57]
	s_add_u32 s56, s56, s48
	s_addc_u32 s57, s57, 0
	global_load_dwordx4 v[100:103], v168, s[56:57]
	s_add_u32 s56, s56, s48
	s_addc_u32 s57, s57, 0
	global_load_dwordx4 v[104:107], v168, s[56:57]
	s_add_u32 s56, s56, s48
	s_addc_u32 s57, s57, 0
	global_load_dwordx4 v[108:111], v168, s[56:57]
	s_add_u32 s56, s56, s48
	s_addc_u32 s57, s57, 0
	global_load_dwordx4 v[112:115], v168, s[56:57]
	s_add_u32 s56, s56, s48
	s_addc_u32 s57, s57, 0
	global_load_dwordx4 v[116:119], v168, s[56:57]
	s_add_u32 s56, s56, s48
	s_addc_u32 s57, s57, 0
	global_load_dwordx4 v[120:123], v168, s[56:57]
	s_add_u32 s56, s56, s48
	s_addc_u32 s57, s57, 0
	global_load_dwordx4 v[124:127], v168, s[56:57]
	s_mov_b32 s59, 1
cvb_pre:
	s_waitcnt vmcnt(0)
cvb_stepA:
	s_cmp_lg_u32 s59, 0
	s_cbranch_scc0 cvb_w0A
	s_waitcnt vmcnt(32)
	s_branch cvb_goA
cvb_w0A:
	s_waitcnt vmcnt(0)
cvb_goA:
	ds_write_b32 v163, v0 offset:0
	ds_write_b32 v163, v1 offset:4
	ds_write_b32 v163, v2 offset:8
	ds_write_b32 v163, v3 offset:12
	ds_write_b32 v163, v4 offset:1040
	ds_write_b32 v163, v5 offset:1044
	ds_write_b32 v163, v6 offset:1048
	ds_write_b32 v163, v7 offset:1052
	ds_write_b32 v163, v8 offset:2080
	ds_write_b32 v163, v9 offset:2084
	ds_write_b32 v163, v10 offset:2088
	ds_write_b32 v163, v11 offset:2092
	ds_write_b32 v163, v12 offset:3120
	ds_write_b32 v163, v13 offset:3124
	ds_write_b32 v163, v14 offset:3128
	ds_write_b32 v163, v15 offset:3132
	ds_write_b32 v163, v16 offset:4160
	ds_write_b32 v163, v17 offset:4164
	ds_write_b32 v163, v18 offset:4168
	ds_write_b32 v163, v19 offset:4172
	ds_write_b32 v163, v20 offset:5200
	ds_write_b32 v163, v21 offset:5204
	ds_write_b32 v163, v22 offset:5208
	ds_write_b32 v163, v23 offset:5212
	ds_write_b32 v163, v24 offset:6240
	ds_write_b32 v163, v25 offset:6244
	ds_write_b32 v163, v26 offset:6248
	ds_write_b32 v163, v27 offset:6252
	ds_write_b32 v163, v28 offset:7280
	ds_write_b32 v163, v29 offset:7284
	ds_write_b32 v163, v30 offset:7288
	ds_write_b32 v163, v31 offset:7292
	ds_write_b32 v163, v32 offset:8320
	ds_write_b32 v163, v33 offset:8324
	ds_write_b32 v163, v34 offset:8328
	ds_write_b32 v163, v35 offset:8332
	ds_write_b32 v163, v36 offset:9360
	ds_write_b32 v163, v37 offset:9364
	ds_write_b32 v163, v38 offset:9368
	ds_write_b32 v163, v39 offset:9372
	ds_write_b32 v163, v40 offset:10400
	ds_write_b32 v163, v41 offset:10404
	ds_write_b32 v163, v42 offset:10408
	ds_write_b32 v163, v43 offset:10412
	ds_write_b32 v163, v44 offset:11440
	ds_write_b32 v163, v45 offset:11444
	ds_write_b32 v163, v46 offset:11448
	ds_write_b32 v163, v47 offset:11452
	ds_write_b32 v163, v48 offset:12480
	ds_write_b32 v163, v49 offset:12484
	ds_write_b32 v163, v50 offset:12488
	ds_write_b32 v163, v51 offset:12492
	ds_write_b32 v163, v52 offset:13520
	ds_write_b32 v163, v53 offset:13524
	ds_write_b32 v163, v54 offset:13528
	ds_write_b32 v163, v55 offset:13532
	ds_write_b32 v163, v56 offset:14560
	ds_write_b32 v163, v57 offset:14564
	ds_write_b32 v163, v58 offset:14568
	ds_write_b32 v163, v59 offset:14572
	ds_write_b32 v163, v60 offset:15600
	ds_write_b32 v163, v61 offset:15604
	ds_write_b32 v163, v62 offset:15608
	ds_write_b32 v163, v63 offset:15612
	s_waitcnt lgkmcnt(0)
	s_mov_b32 s54, s74
	s_mov_b32 s55, s75
	s_lshl_b32 s49, s76, 4
	v_mul_lo_u32 v169, v165, s76
	v_lshl_add_u32 v169, v164, 3, v169
	v_lshlrev_b32_e32 v169, 1, v169
	s_mov_b32 s58, 0
; #define LAS __attribute__((address_space(3)))
; #define LDS_WAIT() asm volatile("s_waitcnt lgkmcnt(0)" ::: "memory")
; __device__ __forceinline__ unsigned pk2(float lo, float hi) { const f32x2c v = {lo, hi}; return __builtin_bit_cast(unsigned, __builtin_convertvector(v, bf16x2c)); }
; __device__ __forceinline__ void tr_store(bf16* dst, int K, const LAS float* scr, int lane) {
;     const int c = lane & 7;
; #pragma unroll
;     for (int j = 0; j < 8; ++j) { const int n = (lane >> 3) + 8 * j; const LAS float* s = scr + (8 * c) * 65 + n;
;         v4u o; o.x = pk2(s[0], s[65]); o.y = pk2(s[130], s[195]); o.z = pk2(s[260], s[325]); o.w = pk2(s[390], s[455]);
;         *(v4u*)(dst + (size_t)n * K + 8 * c) = o; }
;     LDS_WAIT(); asm volatile("" ::: "memory");
; }
; __device__ __forceinline__ void convert_segments(const Args& args, unsigned char* ws, LAS unsigned char* lds, int seg_lo, int seg_hi, int part_lo, int part_hi, int nparts, int wid, int nw, int wave, int lane) {
;     ...
;         for (; it < it_hi; it += nw) {
;             const int kb = it / nblk, nb = it - kb * nblk;
;             const int drow = sg.ilv ? (256 * (nb >> 1) + 64 * (nb & 1) + sg.drow) : (sg.drow + 64 * nb);
;             tr_to_lds(v, scr, lane);
;             const int itn = it + nw;
;             if (itn < it_hi) { const int kbn = itn / nblk, nbn = itn - kbn * nblk; tr_load(W + (size_t)(64 * kbn) * sg.N + sg.scol + 64 * nbn, sg.N, v, lane); }
;             tr_store(WT + (size_t)drow * sg.K + 64 * kb, sg.K, scr, lane);
cvb_nx7:
	s_cmp_lt_u32 s50, s23
	s_cbranch_scc1 cvb_nf7
	s_sub_i32 s50, s50, s23
	s_mov_b32 s23, 0
	s_add_i32 s70, s70, 1
	s_cmp_ge_i32 s70, s61
	s_cbranch_scc1 cvb_nlA
	s_mul_i32 s4, s70, 40
	s_getpc_b64 s[6:7]
	s_add_u32 s6, s6, __const._Z6seg_ati.segs@rel32@lo+4
	s_addc_u32 s7, s7, __const._Z6seg_ati.segs@rel32@hi+12
	s_add_u32 s6, s6, s4
	s_addc_u32 s7, s7, 0
	s_load_dwordx8 s[8:15], s[6:7], 0x0
	s_load_dwordx2 s[18:19], s[6:7], 0x20
	s_waitcnt lgkmcnt(0)
	s_lshr_b32 s20, s13, 6
	s_lshr_b32 s21, s11, 6
	s_mul_i32 s22, s20, s21
	s_lshl_b32 s4, s8, 3
	s_load_dwordx2 s[24:25], s[0:1], s4
	s_mul_i32 s5, s11, s10
	s_mul_i32 s5, s5, s9
	s_lshl_b32 s5, s5, 2
	s_lshl_b32 s6, s12, 2
	s_add_u32 s5, s5, s6
	s_waitcnt lgkmcnt(0)
	s_add_u32 s24, s24, s5
	s_addc_u32 s25, s25, 0
	s_mul_i32 s5, s14, 0x1a400000
	s_lshl_b32 s6, s15, 20
	s_add_u32 s5, s5, s6
	s_add_u32 s5, s5, 0x2d400000
	s_add_u32 s26, s68, s5
	s_addc_u32 s27, s69, 0
	s_lshr_b32 s41, s22, 1
	s_sub_i32 s23, s22, s41
	v_mul_lo_u32 v168, v161, s10
	v_add_u32_e32 v168, v168, v162
	v_lshlrev_b32_e32 v168, 2, v168
	s_lshl_b32 s48, s10, 4
	s_branch cvb_nx7
cvb_nf7:
	s_add_i32 s43, s41, s50
	s_add_i32 s50, s50, s63
	v_cvt_f32_u32_e32 v170, s43
	v_cvt_f32_u32_e32 v171, s20
	v_rcp_f32_e32 v171, v171
	s_nop 1
	v_mul_f32_e32 v170, v170, v171
	v_cvt_u32_f32_e32 v170, v170
	s_nop 1
	v_readfirstlane_b32 s46, v170
	s_mul_i32 s72, s46, s20
	s_sub_i32 s47, s43, s72
	s_cmp_lt_i32 s47, 0
	s_cselect_b32 s72, s20, 0
	s_cselect_b32 s73, 1, 0
	s_add_i32 s47, s47, s72
	s_sub_i32 s46, s46, s73
	s_cmp_ge_i32 s47, s20
	s_cselect_b32 s72, s20, 0
	s_cselect_b32 s73, 1, 0
	s_sub_i32 s47, s47, s72
	s_add_i32 s46, s46, s73
	s_cmp_ge_i32 s47, s20
	s_cselect_b32 s72, s20, 0
	s_cselect_b32 s73, 1, 0
	s_sub_i32 s47, s47, s72
	s_add_i32 s46, s46, s73
	s_mul_i32 s4, s46, s10
	s_add_i32 s4, s4, s47
	s_lshl_b32 s4, s4, 8
	s_add_u32 s56, s24, s4
	s_addc_u32 s57, s25, 0
	s_lshr_b32 s4, s47, 1
	s_lshl_b32 s4, s4, 8
	s_and_b32 s5, s47, 1
	s_lshl_b32 s5, s5, 6
	s_add_i32 s4, s4, s5
	s_lshl_b32 s5, s47, 6
	s_cmp_lg_u32 s19, 0
	s_cselect_b32 s4, s4, s5
	s_add_i32 s4, s4, s18
	s_mul_i32 s4, s4, s11
	s_lshl_b32 s5, s46, 6
	s_add_i32 s4, s4, s5
	s_lshl_b32 s4, s4, 1
	s_add_u32 s74, s26, s4
	s_addc_u32 s75, s27, 0
	s_mov_b32 s76, s11
	global_load_dwordx4 v[0:3], v168, s[56:57]
	s_add_u32 s56, s56, s48
	s_addc_u32 s57, s57, 0
	global_load_dwordx4 v[4:7], v168, s[56:57]
	s_add_u32 s56, s56, s48
	s_addc_u32 s57, s57, 0
	global_load_dwordx4 v[8:11], v168, s[56:57]
	s_add_u32 s56, s56, s48
	s_addc_u32 s57, s57, 0
	global_load_dwordx4 v[12:15], v168, s[56:57]
	s_add_u32 s56, s56, s48
	s_addc_u32 s57, s57, 0
	global_load_dwordx4 v[16:19], v168, s[56:57]
	s_add_u32 s56, s56, s48
	s_addc_u32 s57, s57, 0
	global_load_dwordx4 v[20:23], v168, s[56:57]
	s_add_u32 s56, s56, s48
	s_addc_u32 s57, s57, 0
	global_load_dwordx4 v[24:27], v168, s[56:57]
	s_add_u32 s56, s56, s48
	s_addc_u32 s57, s57, 0
	global_load_dwordx4 v[28:31], v168, s[56:57]
	s_add_u32 s56, s56, s48
	s_addc_u32 s57, s57, 0
	global_load_dwordx4 v[32:35], v168, s[56:57]
	s_add_u32 s56, s56, s48
	s_addc_u32 s57, s57, 0
	global_load_dwordx4 v[36:39], v168, s[56:57]
	s_add_u32 s56, s56, s48
	s_addc_u32 s57, s57, 0
	global_load_dwordx4 v[40:43], v168, s[56:57]
	s_add_u32 s56, s56, s48
	s_addc_u32 s57, s57, 0
	global_load_dwordx4 v[44:47], v168, s[56:57]
	s_add_u32 s56, s56, s48
	s_addc_u32 s57, s57, 0
	global_load_dwordx4 v[48:51], v168, s[56:57]
	s_add_u32 s56, s56, s48
	s_addc_u32 s57, s57, 0
	global_load_dwordx4 v[52:55], v168, s[56:57]
	s_add_u32 s56, s56, s48
	s_addc_u32 s57, s57, 0
	global_load_dwordx4 v[56:59], v168, s[56:57]
	s_add_u32 s56, s56, s48
	s_addc_u32 s57, s57, 0
	global_load_dwordx4 v[60:63], v168, s[56:57]
	s_mov_b32 s58, 1
cvb_nlA:
	ds_read2_b32 v[128:129], v166 offset0:0 offset1:65
	ds_read2_b32 v[130:131], v166 offset0:130 offset1:195
	ds_read2_b32 v[132:133], v167 offset0:0 offset1:65
	ds_read2_b32 v[134:135], v167 offset0:130 offset1:195
	ds_read2_b32 v[136:137], v166 offset0:8 offset1:73
	ds_read2_b32 v[138:139], v166 offset0:138 offset1:203
	ds_read2_b32 v[140:141], v167 offset0:8 offset1:73
	ds_read2_b32 v[142:143], v167 offset0:138 offset1:203
	s_waitcnt lgkmcnt(4)
	v_cvt_pk_bf16_f32 v152, v128, v129
	v_cvt_pk_bf16_f32 v153, v130, v131
	v_cvt_pk_bf16_f32 v154, v132, v133
	v_cvt_pk_bf16_f32 v155, v134, v135
	global_store_dwordx4 v169, v[152:155], s[54:55]
	s_add_u32 s54, s54, s49
	s_addc_u32 s55, s55, 0
	ds_read2_b32 v[144:145], v166 offset0:16 offset1:81
	ds_read2_b32 v[146:147], v166 offset0:146 offset1:211
	ds_read2_b32 v[148:149], v167 offset0:16 offset1:81
	ds_read2_b32 v[150:151], v167 offset0:146 offset1:211
	s_waitcnt lgkmcnt(4)
	v_cvt_pk_bf16_f32 v156, v136, v137
	v_cvt_pk_bf16_f32 v157, v138, v139
	v_cvt_pk_bf16_f32 v158, v140, v141
	v_cvt_pk_bf16_f32 v159, v142, v143
	global_store_dwordx4 v169, v[156:159], s[54:55]
	s_add_u32 s54, s54, s49
	s_addc_u32 s55, s55, 0
	ds_read2_b32 v[128:129], v166 offset0:24 offset1:89
	ds_read2_b32 v[130:131], v166 offset0:154 offset1:219
	ds_read2_b32 v[132:133], v167 offset0:24 offset1:89
	ds_read2_b32 v[134:135], v167 offset0:154 offset1:219
	s_waitcnt lgkmcnt(4)
	v_cvt_pk_bf16_f32 v152, v144, v145
	v_cvt_pk_bf16_f32 v153, v146, v147
	v_cvt_pk_bf16_f32 v154, v148, v149
	v_cvt_pk_bf16_f32 v155, v150, v151
	global_store_dwordx4 v169, v[152:155], s[54:55]
	s_add_u32 s54, s54, s49
	s_addc_u32 s55, s55, 0
	ds_read2_b32 v[136:137], v166 offset0:32 offset1:97
	ds_read2_b32 v[138:139], v166 offset0:162 offset1:227
	ds_read2_b32 v[140:141], v167 offset0:32 offset1:97
	ds_read2_b32 v[142:143], v167 offset0:162 offset1:227
	s_waitcnt lgkmcnt(4)
; #define LAS __attribute__((address_space(3)))
; #define LDS_WAIT() asm volatile("s_waitcnt lgkmcnt(0)" ::: "memory")
; __device__ __forceinline__ unsigned pk2(float lo, float hi) { const f32x2c v = {lo, hi}; return __builtin_bit_cast(unsigned, __builtin_convertvector(v, bf16x2c)); }
; __device__ __forceinline__ void tr_to_lds(const f32x4 (&v)[16], LAS float* scr, int lane) {
;     const int r4 = lane >> 4, c4 = (lane & 15) * 4;
; #pragma unroll
;     for (int i = 0; i < 16; ++i) { LAS float* s = scr + (4 * i + r4) * 65 + c4; s[0] = v[i].x; s[1] = v[i].y; s[2] = v[i].z; s[3] = v[i].w; }
;     LDS_WAIT(); asm volatile("" ::: "memory");
; }
; __device__ __forceinline__ void tr_store(bf16* dst, int K, const LAS float* scr, int lane) {
;     const int c = lane & 7;
; #pragma unroll
;     for (int j = 0; j < 8; ++j) { const int n = (lane >> 3) + 8 * j; const LAS float* s = scr + (8 * c) * 65 + n;
;         v4u o; o.x = pk2(s[0], s[65]); o.y = pk2(s[130], s[195]); o.z = pk2(s[260], s[325]); o.w = pk2(s[390], s[455]);
;         *(v4u*)(dst + (size_t)n * K + 8 * c) = o; }
;     LDS_WAIT(); asm volatile("" ::: "memory");
; }
	v_cvt_pk_bf16_f32 v156, v128, v129
	v_cvt_pk_bf16_f32 v157, v130, v131
	v_cvt_pk_bf16_f32 v158, v132, v133
	v_cvt_pk_bf16_f32 v159, v134, v135
	global_store_dwordx4 v169, v[156:159], s[54:55]
	s_add_u32 s54, s54, s49
	s_addc_u32 s55, s55, 0
	ds_read2_b32 v[144:145], v166 offset0:40 offset1:105
	ds_read2_b32 v[146:147], v166 offset0:170 offset1:235
	ds_read2_b32 v[148:149], v167 offset0:40 offset1:105
	ds_read2_b32 v[150:151], v167 offset0:170 offset1:235
	s_waitcnt lgkmcnt(4)
	v_cvt_pk_bf16_f32 v152, v136, v137
	v_cvt_pk_bf16_f32 v153, v138, v139
	v_cvt_pk_bf16_f32 v154, v140, v141
	v_cvt_pk_bf16_f32 v155, v142, v143
	global_store_dwordx4 v169, v[152:155], s[54:55]
	s_add_u32 s54, s54, s49
	s_addc_u32 s55, s55, 0
	ds_read2_b32 v[128:129], v166 offset0:48 offset1:113
	ds_read2_b32 v[130:131], v166 offset0:178 offset1:243
	ds_read2_b32 v[132:133], v167 offset0:48 offset1:113
	ds_read2_b32 v[134:135], v167 offset0:178 offset1:243
	s_waitcnt lgkmcnt(4)
	v_cvt_pk_bf16_f32 v156, v144, v145
	v_cvt_pk_bf16_f32 v157, v146, v147
	v_cvt_pk_bf16_f32 v158, v148, v149
	v_cvt_pk_bf16_f32 v159, v150, v151
	global_store_dwordx4 v169, v[156:159], s[54:55]
	s_add_u32 s54, s54, s49
	s_addc_u32 s55, s55, 0
	ds_read2_b32 v[136:137], v166 offset0:56 offset1:121
	ds_read2_b32 v[138:139], v166 offset0:186 offset1:251
	ds_read2_b32 v[140:141], v167 offset0:56 offset1:121
	ds_read2_b32 v[142:143], v167 offset0:186 offset1:251
	s_waitcnt lgkmcnt(4)
	v_cvt_pk_bf16_f32 v152, v128, v129
	v_cvt_pk_bf16_f32 v153, v130, v131
	v_cvt_pk_bf16_f32 v154, v132, v133
	v_cvt_pk_bf16_f32 v155, v134, v135
	global_store_dwordx4 v169, v[152:155], s[54:55]
	s_add_u32 s54, s54, s49
	s_addc_u32 s55, s55, 0
	s_waitcnt lgkmcnt(0)
	v_cvt_pk_bf16_f32 v156, v136, v137
	v_cvt_pk_bf16_f32 v157, v138, v139
	v_cvt_pk_bf16_f32 v158, v140, v141
	v_cvt_pk_bf16_f32 v159, v142, v143
	global_store_dwordx4 v169, v[156:159], s[54:55]
	s_cmp_lg_u32 s59, 0
	s_cbranch_scc0 cvb_done
cvb_stepB:
	s_cmp_lg_u32 s58, 0
	s_cbranch_scc0 cvb_w0B
	s_waitcnt vmcnt(32)
	s_branch cvb_goB
cvb_w0B:
	s_waitcnt vmcnt(0)
cvb_goB:
	ds_write_b32 v163, v64 offset:0
	ds_write_b32 v163, v65 offset:4
	ds_write_b32 v163, v66 offset:8
	ds_write_b32 v163, v67 offset:12
	ds_write_b32 v163, v68 offset:1040
	ds_write_b32 v163, v69 offset:1044
	ds_write_b32 v163, v70 offset:1048
	ds_write_b32 v163, v71 offset:1052
	ds_write_b32 v163, v72 offset:2080
	ds_write_b32 v163, v73 offset:2084
	ds_write_b32 v163, v74 offset:2088
	ds_write_b32 v163, v75 offset:2092
	ds_write_b32 v163, v76 offset:3120
	ds_write_b32 v163, v77 offset:3124
	ds_write_b32 v163, v78 offset:3128
	ds_write_b32 v163, v79 offset:3132
	ds_write_b32 v163, v80 offset:4160
	ds_write_b32 v163, v81 offset:4164
	ds_write_b32 v163, v82 offset:4168
	ds_write_b32 v163, v83 offset:4172
	ds_write_b32 v163, v84 offset:5200
	ds_write_b32 v163, v85 offset:5204
	ds_write_b32 v163, v86 offset:5208
	ds_write_b32 v163, v87 offset:5212
	ds_write_b32 v163, v88 offset:6240
	ds_write_b32 v163, v89 offset:6244
	ds_write_b32 v163, v90 offset:6248
	ds_write_b32 v163, v91 offset:6252
	ds_write_b32 v163, v92 offset:7280
	ds_write_b32 v163, v93 offset:7284
	ds_write_b32 v163, v94 offset:7288
	ds_write_b32 v163, v95 offset:7292
	ds_write_b32 v163, v96 offset:8320
	ds_write_b32 v163, v97 offset:8324
	ds_write_b32 v163, v98 offset:8328
	ds_write_b32 v163, v99 offset:8332
	ds_write_b32 v163, v100 offset:9360
	ds_write_b32 v163, v101 offset:9364
	ds_write_b32 v163, v102 offset:9368
	ds_write_b32 v163, v103 offset:9372
	ds_write_b32 v163, v104 offset:10400
	ds_write_b32 v163, v105 offset:10404
	ds_write_b32 v163, v106 offset:10408
	ds_write_b32 v163, v107 offset:10412
	ds_write_b32 v163, v108 offset:11440
	ds_write_b32 v163, v109 offset:11444
	ds_write_b32 v163, v110 offset:11448
	ds_write_b32 v163, v111 offset:11452
	ds_write_b32 v163, v112 offset:12480
	ds_write_b32 v163, v113 offset:12484
	ds_write_b32 v163, v114 offset:12488
	ds_write_b32 v163, v115 offset:12492
	ds_write_b32 v163, v116 offset:13520
	ds_write_b32 v163, v117 offset:13524
	ds_write_b32 v163, v118 offset:13528
	ds_write_b32 v163, v119 offset:13532
	ds_write_b32 v163, v120 offset:14560
	ds_write_b32 v163, v121 offset:14564
	ds_write_b32 v163, v122 offset:14568
	ds_write_b32 v163, v123 offset:14572
	ds_write_b32 v163, v124 offset:15600
	ds_write_b32 v163, v125 offset:15604
	ds_write_b32 v163, v126 offset:15608
	ds_write_b32 v163, v127 offset:15612
	s_waitcnt lgkmcnt(0)
	s_mov_b32 s54, s78
	s_mov_b32 s55, s79
	s_lshl_b32 s49, s77, 4
	v_mul_lo_u32 v169, v165, s77
	v_lshl_add_u32 v169, v164, 3, v169
	v_lshlrev_b32_e32 v169, 1, v169
	s_mov_b32 s59, 0
cvb_nx8:
	s_cmp_lt_u32 s50, s23
	s_cbranch_scc1 cvb_nf8
	s_sub_i32 s50, s50, s23
	s_mov_b32 s23, 0
	s_add_i32 s70, s70, 1
	s_cmp_ge_i32 s70, s61
	s_cbranch_scc1 cvb_nlB
	s_mul_i32 s4, s70, 40
	s_getpc_b64 s[6:7]
	s_add_u32 s6, s6, __const._Z6seg_ati.segs@rel32@lo+4
	s_addc_u32 s7, s7, __const._Z6seg_ati.segs@rel32@hi+12
	s_add_u32 s6, s6, s4
	s_addc_u32 s7, s7, 0
	s_load_dwordx8 s[8:15], s[6:7], 0x0
	s_load_dwordx2 s[18:19], s[6:7], 0x20
	s_waitcnt lgkmcnt(0)
	s_lshr_b32 s20, s13, 6
	s_lshr_b32 s21, s11, 6
	s_mul_i32 s22, s20, s21
	s_lshl_b32 s4, s8, 3
	s_load_dwordx2 s[24:25], s[0:1], s4
	s_mul_i32 s5, s11, s10
	s_mul_i32 s5, s5, s9
	s_lshl_b32 s5, s5, 2
	s_lshl_b32 s6, s12, 2
	s_add_u32 s5, s5, s6
	s_waitcnt lgkmcnt(0)
	s_add_u32 s24, s24, s5
	s_addc_u32 s25, s25, 0
	s_mul_i32 s5, s14, 0x1a400000
	s_lshl_b32 s6, s15, 20
	s_add_u32 s5, s5, s6
	s_add_u32 s5, s5, 0x2d400000
	s_add_u32 s26, s68, s5
	s_addc_u32 s27, s69, 0
	s_lshr_b32 s41, s22, 1
	s_sub_i32 s23, s22, s41
	v_mul_lo_u32 v168, v161, s10
	v_add_u32_e32 v168, v168, v162
	v_lshlrev_b32_e32 v168, 2, v168
	s_lshl_b32 s48, s10, 4
	s_branch cvb_nx8
; #define LAS __attribute__((address_space(3)))
; #define LDS_WAIT() asm volatile("s_waitcnt lgkmcnt(0)" ::: "memory")
; __device__ __forceinline__ unsigned pk2(float lo, float hi) { const f32x2c v = {lo, hi}; return __builtin_bit_cast(unsigned, __builtin_convertvector(v, bf16x2c)); }
; __device__ __forceinline__ void tr_load(const float* src, int N, f32x4 (&v)[16], int lane) {
;     const int r4 = lane >> 4, c4 = (lane & 15) * 4;
; #pragma unroll
;     for (int i = 0; i < 16; ++i) v[i] = *(const f32x4*)(src + (size_t)(4 * i + r4) * N + c4);
; }
; __device__ __forceinline__ void tr_to_lds(const f32x4 (&v)[16], LAS float* scr, int lane) {
;     const int r4 = lane >> 4, c4 = (lane & 15) * 4;
; #pragma unroll
;     for (int i = 0; i < 16; ++i) { LAS float* s = scr + (4 * i + r4) * 65 + c4; s[0] = v[i].x; s[1] = v[i].y; s[2] = v[i].z; s[3] = v[i].w; }
;     LDS_WAIT(); asm volatile("" ::: "memory");
; }
; __device__ __forceinline__ void tr_store(bf16* dst, int K, const LAS float* scr, int lane) {
;     const int c = lane & 7;
; #pragma unroll
;     for (int j = 0; j < 8; ++j) { const int n = (lane >> 3) + 8 * j; const LAS float* s = scr + (8 * c) * 65 + n;
;         v4u o; o.x = pk2(s[0], s[65]); o.y = pk2(s[130], s[195]); o.z = pk2(s[260], s[325]); o.w = pk2(s[390], s[455]);
;         *(v4u*)(dst + (size_t)n * K + 8 * c) = o; }
;     LDS_WAIT(); asm volatile("" ::: "memory");
; }
cvb_nf8:
	s_add_i32 s43, s41, s50
	s_add_i32 s50, s50, s63
	v_cvt_f32_u32_e32 v170, s43
	v_cvt_f32_u32_e32 v171, s20
	v_rcp_f32_e32 v171, v171
	s_nop 1
	v_mul_f32_e32 v170, v170, v171
	v_cvt_u32_f32_e32 v170, v170
	s_nop 1
	v_readfirstlane_b32 s46, v170
	s_mul_i32 s72, s46, s20
	s_sub_i32 s47, s43, s72
	s_cmp_lt_i32 s47, 0
	s_cselect_b32 s72, s20, 0
	s_cselect_b32 s73, 1, 0
	s_add_i32 s47, s47, s72
	s_sub_i32 s46, s46, s73
	s_cmp_ge_i32 s47, s20
	s_cselect_b32 s72, s20, 0
	s_cselect_b32 s73, 1, 0
	s_sub_i32 s47, s47, s72
	s_add_i32 s46, s46, s73
	s_cmp_ge_i32 s47, s20
	s_cselect_b32 s72, s20, 0
	s_cselect_b32 s73, 1, 0
	s_sub_i32 s47, s47, s72
	s_add_i32 s46, s46, s73
	s_mul_i32 s4, s46, s10
	s_add_i32 s4, s4, s47
	s_lshl_b32 s4, s4, 8
	s_add_u32 s56, s24, s4
	s_addc_u32 s57, s25, 0
	s_lshr_b32 s4, s47, 1
	s_lshl_b32 s4, s4, 8
	s_and_b32 s5, s47, 1
	s_lshl_b32 s5, s5, 6
	s_add_i32 s4, s4, s5
	s_lshl_b32 s5, s47, 6
	s_cmp_lg_u32 s19, 0
	s_cselect_b32 s4, s4, s5
	s_add_i32 s4, s4, s18
	s_mul_i32 s4, s4, s11
	s_lshl_b32 s5, s46, 6
	s_add_i32 s4, s4, s5
	s_lshl_b32 s4, s4, 1
	s_add_u32 s78, s26, s4
	s_addc_u32 s79, s27, 0
	s_mov_b32 s77, s11
	global_load_dwordx4 v[64:67], v168, s[56:57]
	s_add_u32 s56, s56, s48
	s_addc_u32 s57, s57, 0
	global_load_dwordx4 v[68:71], v168, s[56:57]
	s_add_u32 s56, s56, s48
	s_addc_u32 s57, s57, 0
	global_load_dwordx4 v[72:75], v168, s[56:57]
	s_add_u32 s56, s56, s48
	s_addc_u32 s57, s57, 0
	global_load_dwordx4 v[76:79], v168, s[56:57]
	s_add_u32 s56, s56, s48
	s_addc_u32 s57, s57, 0
	global_load_dwordx4 v[80:83], v168, s[56:57]
	s_add_u32 s56, s56, s48
	s_addc_u32 s57, s57, 0
	global_load_dwordx4 v[84:87], v168, s[56:57]
	s_add_u32 s56, s56, s48
	s_addc_u32 s57, s57, 0
	global_load_dwordx4 v[88:91], v168, s[56:57]
	s_add_u32 s56, s56, s48
	s_addc_u32 s57, s57, 0
	global_load_dwordx4 v[92:95], v168, s[56:57]
	s_add_u32 s56, s56, s48
	s_addc_u32 s57, s57, 0
	global_load_dwordx4 v[96:99], v168, s[56:57]
	s_add_u32 s56, s56, s48
	s_addc_u32 s57, s57, 0
	global_load_dwordx4 v[100:103], v168, s[56:57]
	s_add_u32 s56, s56, s48
	s_addc_u32 s57, s57, 0
	global_load_dwordx4 v[104:107], v168, s[56:57]
	s_add_u32 s56, s56, s48
	s_addc_u32 s57, s57, 0
	global_load_dwordx4 v[108:111], v168, s[56:57]
	s_add_u32 s56, s56, s48
	s_addc_u32 s57, s57, 0
	global_load_dwordx4 v[112:115], v168, s[56:57]
	s_add_u32 s56, s56, s48
	s_addc_u32 s57, s57, 0
	global_load_dwordx4 v[116:119], v168, s[56:57]
	s_add_u32 s56, s56, s48
	s_addc_u32 s57, s57, 0
	global_load_dwordx4 v[120:123], v168, s[56:57]
	s_add_u32 s56, s56, s48
	s_addc_u32 s57, s57, 0
	global_load_dwordx4 v[124:127], v168, s[56:57]
	s_mov_b32 s59, 1
cvb_nlB:
	ds_read2_b32 v[128:129], v166 offset0:0 offset1:65
	ds_read2_b32 v[130:131], v166 offset0:130 offset1:195
	ds_read2_b32 v[132:133], v167 offset0:0 offset1:65
	ds_read2_b32 v[134:135], v167 offset0:130 offset1:195
	ds_read2_b32 v[136:137], v166 offset0:8 offset1:73
	ds_read2_b32 v[138:139], v166 offset0:138 offset1:203
	ds_read2_b32 v[140:141], v167 offset0:8 offset1:73
	ds_read2_b32 v[142:143], v167 offset0:138 offset1:203
	s_waitcnt lgkmcnt(4)
	v_cvt_pk_bf16_f32 v152, v128, v129
	v_cvt_pk_bf16_f32 v153, v130, v131
	v_cvt_pk_bf16_f32 v154, v132, v133
	v_cvt_pk_bf16_f32 v155, v134, v135
	global_store_dwordx4 v169, v[152:155], s[54:55]
	s_add_u32 s54, s54, s49
	s_addc_u32 s55, s55, 0
	ds_read2_b32 v[144:145], v166 offset0:16 offset1:81
	ds_read2_b32 v[146:147], v166 offset0:146 offset1:211
	ds_read2_b32 v[148:149], v167 offset0:16 offset1:81
	ds_read2_b32 v[150:151], v167 offset0:146 offset1:211
	s_waitcnt lgkmcnt(4)
	v_cvt_pk_bf16_f32 v156, v136, v137
	v_cvt_pk_bf16_f32 v157, v138, v139
	v_cvt_pk_bf16_f32 v158, v140, v141
	v_cvt_pk_bf16_f32 v159, v142, v143
	global_store_dwordx4 v169, v[156:159], s[54:55]
	s_add_u32 s54, s54, s49
	s_addc_u32 s55, s55, 0
	ds_read2_b32 v[128:129], v166 offset0:24 offset1:89
	ds_read2_b32 v[130:131], v166 offset0:154 offset1:219
	ds_read2_b32 v[132:133], v167 offset0:24 offset1:89
	ds_read2_b32 v[134:135], v167 offset0:154 offset1:219
	s_waitcnt lgkmcnt(4)
	v_cvt_pk_bf16_f32 v152, v144, v145
	v_cvt_pk_bf16_f32 v153, v146, v147
	v_cvt_pk_bf16_f32 v154, v148, v149
	v_cvt_pk_bf16_f32 v155, v150, v151
	global_store_dwordx4 v169, v[152:155], s[54:55]
	s_add_u32 s54, s54, s49
	s_addc_u32 s55, s55, 0
	ds_read2_b32 v[136:137], v166 offset0:32 offset1:97
	ds_read2_b32 v[138:139], v166 offset0:162 offset1:227
	ds_read2_b32 v[140:141], v167 offset0:32 offset1:97
	ds_read2_b32 v[142:143], v167 offset0:162 offset1:227
	s_waitcnt lgkmcnt(4)
	v_cvt_pk_bf16_f32 v156, v128, v129
	v_cvt_pk_bf16_f32 v157, v130, v131
	v_cvt_pk_bf16_f32 v158, v132, v133
	v_cvt_pk_bf16_f32 v159, v134, v135
	global_store_dwordx4 v169, v[156:159], s[54:55]
	s_add_u32 s54, s54, s49
	s_addc_u32 s55, s55, 0
	ds_read2_b32 v[144:145], v166 offset0:40 offset1:105
	ds_read2_b32 v[146:147], v166 offset0:170 offset1:235
	ds_read2_b32 v[148:149], v167 offset0:40 offset1:105
	ds_read2_b32 v[150:151], v167 offset0:170 offset1:235
	s_waitcnt lgkmcnt(4)
	v_cvt_pk_bf16_f32 v152, v136, v137
	v_cvt_pk_bf16_f32 v153, v138, v139
	v_cvt_pk_bf16_f32 v154, v140, v141
	v_cvt_pk_bf16_f32 v155, v142, v143
	global_store_dwordx4 v169, v[152:155], s[54:55]
	s_add_u32 s54, s54, s49
	s_addc_u32 s55, s55, 0
	ds_read2_b32 v[128:129], v166 offset0:48 offset1:113
	ds_read2_b32 v[130:131], v166 offset0:178 offset1:243
	ds_read2_b32 v[132:133], v167 offset0:48 offset1:113
	ds_read2_b32 v[134:135], v167 offset0:178 offset1:243
	s_waitcnt lgkmcnt(4)
	v_cvt_pk_bf16_f32 v156, v144, v145
	v_cvt_pk_bf16_f32 v157, v146, v147
	v_cvt_pk_bf16_f32 v158, v148, v149
	v_cvt_pk_bf16_f32 v159, v150, v151
	global_store_dwordx4 v169, v[156:159], s[54:55]
	s_add_u32 s54, s54, s49
	s_addc_u32 s55, s55, 0
	ds_read2_b32 v[136:137], v166 offset0:56 offset1:121
	ds_read2_b32 v[138:139], v166 offset0:186 offset1:251
	ds_read2_b32 v[140:141], v167 offset0:56 offset1:121
	ds_read2_b32 v[142:143], v167 offset0:186 offset1:251
	s_waitcnt lgkmcnt(4)
	v_cvt_pk_bf16_f32 v152, v128, v129
	v_cvt_pk_bf16_f32 v153, v130, v131
	v_cvt_pk_bf16_f32 v154, v132, v133
	v_cvt_pk_bf16_f32 v155, v134, v135
	global_store_dwordx4 v169, v[152:155], s[54:55]
	s_add_u32 s54, s54, s49
	s_addc_u32 s55, s55, 0
	s_waitcnt lgkmcnt(0)
	v_cvt_pk_bf16_f32 v156, v136, v137
	v_cvt_pk_bf16_f32 v157, v138, v139
	v_cvt_pk_bf16_f32 v158, v140, v141
	v_cvt_pk_bf16_f32 v159, v142, v143
	global_store_dwordx4 v169, v[156:159], s[54:55]
	s_cmp_lg_u32 s58, 0
	s_cbranch_scc0 cvb_done
	s_branch cvb_stepA
cvb_done:
	s_waitcnt vmcnt(0) lgkmcnt(0)
